# EpiResid epilogues (W_out, cross_wo): bf16 output stores widened to dwordx4 via v_permlane16_swap
# speedup vs baseline: 1.0257x; 1.0257x over previous
; #define LAS __attribute__((address_space(3)))
; __device__ __forceinline__ void row_stats_table(LAS unsigned char* lds, const float* ST, int pm) {
;     const int tid = threadIdx.x;
;     if (tid < 256) { const GASP f32x4* sp = (const GASP f32x4*)(ST + (size_t)(pm * BM + tid) * 32); float s = 0.f, q = 0.f;
; #pragma unroll
;         for (int i = 0; i < 8; ++i) { const f32x4 v = sp[i]; s += v[0] + v[2]; q += v[1] + v[3]; }
;         const float mu = s * (1.f / D), var = q * (1.f / D) - mu * mu;
;         ((LAS f32x2*)(lds + SL_OFF))[tid] = (f32x2){mu, 1.f / sqrtf(var + LN_EPS)}; }
;     asm volatile("s_waitcnt lgkmcnt(0)" ::: "memory"); __builtin_amdgcn_s_barrier(); asm volatile("" ::: "memory");
; }
;     __device__ __forceinline__ void operator()(Acc& acc, const Unit& u, int wr, int wc, int fr, int fq, LAS unsigned char* lds) const {
;         const int col0 = u.pn * BM + wc * 32 + 4 * fq;
;         if (STp) row_stats_table(lds, STp, u.pm);
;         const LAS f32x2* SL = (const LAS f32x2*)(lds + SL_OFF);
;         f32x4 gg[2][2], bb[2][2];
;         if (STp) {
; #pragma unroll
;             for (int bj = 0; bj < 2; ++bj)
; #pragma unroll
;                 for (int n = 0; n < 2; ++n) { gg[bj][n] = *(const GASP f32x4*)(gam + col0 + bj * HALF + n * 16); bb[bj][n] = *(const GASP f32x4*)(bet + col0 + bj * HALF + n * 16); }
;         }
; #pragma unroll
;         for (int ai = 0; ai < 2; ++ai)
; #pragma unroll
;             for (int m = 0; m < 4; ++m) {
;                 const int rl = ai * HALF + wr * 64 + m * 16 + fr, row = u.pm * BM + rl;
;                 const float* rp = (row < split) ? res0 + (size_t)row * D : res1 + (size_t)(row - split) * D;
;                 float* op = out + (size_t)row * D;
;                 f32x2 st = (f32x2){0.f, 1.f}; if (STp) st = SL[rl];
;                 float s = 0.f, q = 0.f;
; #pragma unroll
;                 for (int bj = 0; bj < 2; ++bj)
; #pragma unroll
;                     for (int n = 0; n < 2; ++n) { const int c = col0 + bj * HALF + n * 16; f32x4 r;
;                         if (resb) { const u32x2 w = *(const GASP u32x2*)(resb + (size_t)row * D + c);
;                             r = (f32x4){__uint_as_float(w.x << 16), __uint_as_float(w.x & 0xffff0000u), __uint_as_float(w.y << 16), __uint_as_float(w.y & 0xffff0000u)}; }
;                         else r = *(const GASP f32x4*)(rp + c);
.LBB0_1042:
	s_lshl_b32 s37, s14, 8
	v_bfe_u32 v246, v203, 4, 1
	v_mul_u32_u24_e32 v246, 24, v246
	v_mov_b32_e32 v247, 0
	s_and_saveexec_b64 s[60:61], s[6:7]
	s_cbranch_execz .LBB0_1044
	v_or_b32_e32 v64, s37, v208
	v_ashrrev_i32_e32 v65, 31, v64
	v_lshlrev_b64 v[64:65], 7, v[64:65]
	v_lshl_add_u64 v[92:93], s[22:23], 0, v[64:65]
	global_load_dwordx4 v[64:67], v[92:93], off
	global_load_dwordx4 v[68:71], v[92:93], off offset:16
	global_load_dwordx4 v[72:75], v[92:93], off offset:32
	global_load_dwordx4 v[76:79], v[92:93], off offset:48
	global_load_dwordx4 v[80:83], v[92:93], off offset:64
	global_load_dwordx4 v[84:87], v[92:93], off offset:80
	global_load_dwordx4 v[88:91], v[92:93], off offset:96
	s_nop 0
	global_load_dwordx4 v[92:95], v[92:93], off offset:112
	s_waitcnt vmcnt(0)
	v_pk_add_f32 v[64:65], v[64:65], v[66:67]
	v_pk_add_f32 v[66:67], v[68:69], v[70:71]
	v_pk_add_f32 v[64:65], v[64:65], 0 op_sel_hi:[1,0]
	v_pk_add_f32 v[68:69], v[72:73], v[74:75]
	v_pk_add_f32 v[64:65], v[64:65], v[66:67]
	v_pk_add_f32 v[70:71], v[76:77], v[78:79]
	v_pk_add_f32 v[64:65], v[64:65], v[68:69]
	v_pk_add_f32 v[72:73], v[80:81], v[82:83]
	v_pk_add_f32 v[64:65], v[64:65], v[70:71]
	v_pk_add_f32 v[74:75], v[84:85], v[86:87]
	v_pk_add_f32 v[64:65], v[64:65], v[72:73]
	v_pk_add_f32 v[76:77], v[88:89], v[90:91]
	v_pk_add_f32 v[64:65], v[64:65], v[74:75]
	v_pk_add_f32 v[78:79], v[92:93], v[94:95]
	v_pk_add_f32 v[64:65], v[64:65], v[76:77]
	s_nop 0
	v_pk_add_f32 v[64:65], v[64:65], v[78:79]
	s_nop 0
	v_pk_mul_f32 v[64:65], v[64:65], s[30:31] op_sel_hi:[1,0]
	s_nop 0
	v_fma_f32 v65, -v64, v64, v65
	v_add_f32_e32 v65, 0x3727c5ac, v65
	v_mul_f32_e32 v66, 0x4f800000, v65
	v_cmp_gt_f32_e32 vcc, s72, v65
	s_nop 1
	v_cndmask_b32_e32 v65, v65, v66, vcc
	v_sqrt_f32_e32 v66, v65
	s_nop 0
	v_add_u32_e32 v67, -1, v66
	v_add_u32_e32 v68, 1, v66
	v_fma_f32 v69, -v67, v66, v65
	v_fma_f32 v70, -v68, v66, v65
	v_cmp_ge_f32_e64 s[14:15], 0, v69
	s_nop 1
	v_cndmask_b32_e64 v66, v66, v67, s[14:15]
	v_cmp_lt_f32_e64 s[14:15], 0, v70
	s_nop 1
	v_cndmask_b32_e64 v66, v66, v68, s[14:15]
	v_mul_f32_e32 v67, 0x37800000, v66
	v_cndmask_b32_e32 v66, v66, v67, vcc
	v_cmp_class_f32_e32 vcc, v65, v202
	s_nop 1
	v_cndmask_b32_e32 v65, v66, v65, vcc
	v_div_scale_f32 v66, s[14:15], v65, v65, 1.0
	v_rcp_f32_e32 v67, v66
	v_div_scale_f32 v68, vcc, 1.0, v65, 1.0
	v_fma_f32 v69, -v66, v67, 1.0
	v_fmac_f32_e32 v67, v69, v67
	v_mul_f32_e32 v69, v68, v67
	v_fma_f32 v70, -v66, v69, v68
	v_fmac_f32_e32 v69, v70, v67
	v_fma_f32 v66, -v66, v69, v68
	v_div_fmas_f32 v66, v66, v67, v69
	v_div_fixup_f32 v65, v66, v65, 1.0
	ds_write_b64 v183, v[64:65]
.LBB0_1044:
	s_or_b64 exec, exec, s[60:61]
	v_add_u32_e32 v176, s37, v180
	v_ashrrev_i32_e32 v64, 31, v176
	v_cmp_gt_i32_e32 vcc, s73, v176
	v_lshl_or_b32 v174, s50, 8, v182
	v_ashrrev_i32_e32 v175, 31, v174
	v_cndmask_b32_e32 v177, 0, v64, vcc
	v_lshlrev_b64 v[64:65], 11, v[176:177]
	v_lshl_add_u64 v[64:65], s[42:43], 0, v[64:65]
	s_waitcnt lgkmcnt(0)
	s_barrier
	v_lshl_add_u64 v[178:179], v[174:175], 1, v[64:65]
	global_load_dwordx2 v[204:205], v[178:179], off
	global_load_dwordx2 v[206:207], v[178:179], off offset:32
	global_load_dwordx2 v[210:211], v[178:179], off offset:256
	v_lshlrev_b64 v[64:65], 2, v[174:175]
	v_lshl_add_u64 v[92:93], s[18:19], 0, v[64:65]
	v_lshl_add_u64 v[88:89], s[16:17], 0, v[64:65]
	global_load_dwordx4 v[64:67], v[92:93], off
	global_load_dwordx4 v[76:79], v[88:89], off
	global_load_dwordx4 v[68:71], v[88:89], off offset:64
	global_load_dwordx4 v[80:83], v[92:93], off offset:64
	global_load_dwordx4 v[72:75], v[88:89], off offset:512
	global_load_dwordx4 v[84:87], v[92:93], off offset:512
	global_load_dwordx2 v[212:213], v[178:179], off offset:288
	ds_read_b64 v[214:215], v184
	global_load_dwordx4 v[88:91], v[88:89], off offset:576
	s_nop 0
	global_load_dwordx4 v[92:95], v[92:93], off offset:576
	s_lshl_b32 s14, s50, 3
	s_or_b32 s14, s14, s69
	s_ashr_i32 s15, s14, 31
	s_waitcnt vmcnt(0)
	v_lshlrev_b32_e32 v165, 16, v204
	v_and_b32_e32 v204, 0xffff0000, v204
	v_lshlrev_b32_e32 v216, 16, v205
	v_and_b32_e32 v217, 0xffff0000, v205
	v_lshlrev_b32_e32 v222, 16, v206
	v_and_b32_e32 v223, 0xffff0000, v206
	v_lshlrev_b32_e32 v224, 16, v207
	v_and_b32_e32 v225, 0xffff0000, v207
	v_lshlrev_b32_e32 v226, 16, v210
	v_and_b32_e32 v227, 0xffff0000, v210
	v_lshlrev_b32_e32 v228, 16, v211
	v_and_b32_e32 v229, 0xffff0000, v211
	s_waitcnt lgkmcnt(0)
; #define GASP __attribute__((address_space(1)))
;     __device__ __forceinline__ void operator()(Acc& acc, const Unit& u, int wr, int wc, int fr, int fq, LAS unsigned char* lds) const {
;     ...
;                 const int rl = ai * HALF + wr * 64 + m * 16 + fr, row = u.pm * BM + rl;
;                 const float* rp = (row < split) ? res0 + (size_t)row * D : res1 + (size_t)(row - split) * D;
;                 float* op = out + (size_t)row * D;
;                 f32x2 st = (f32x2){0.f, 1.f}; if (STp) st = SL[rl];
;                 float s = 0.f, q = 0.f;
; #pragma unroll
;                 for (int bj = 0; bj < 2; ++bj)
; #pragma unroll
;                     for (int n = 0; n < 2; ++n) { const int c = col0 + bj * HALF + n * 16; f32x4 r;
;                         if (resb) { const u32x2 w = *(const GASP u32x2*)(resb + (size_t)row * D + c);
;                             r = (f32x4){__uint_as_float(w.x << 16), __uint_as_float(w.x & 0xffff0000u), __uint_as_float(w.y << 16), __uint_as_float(w.y & 0xffff0000u)}; }
;                         else r = *(const GASP f32x4*)(rp + c);
;                         if (STp) r = (r - st[0]) * st[1] * gg[bj][n] + bb[bj][n];
;                         const f32x4 o = r * ALPHA + acc[ai][bj][m][n] * scale;
;                         if (out) *(GASP f32x4*)(op + c) = o;
;                         if (ob) { u32x2 w; w.x = pk2(o[0], o[1]); w.y = pk2(o[2], o[3]); *(GASP u32x2*)(ob + (size_t)row * D + c) = w; }
;                         s += (o[0] + o[1]) + (o[2] + o[3]); q += (o[0] * o[0] + o[1] * o[1]) + (o[2] * o[2] + o[3] * o[3]); }
;                 if (STn) { s += __shfl_xor(s, 16); s += __shfl_xor(s, 32); q += __shfl_xor(q, 16); q += __shfl_xor(q, 32);
;                     if (fq == 0) *(GASP f32x2*)(STn + (size_t)row * 32 + (u.pn * 4 + wc) * 2) = (f32x2){s, q}; }
	v_sub_f32_e32 v205, v204, v214
	v_sub_f32_e32 v204, v165, v214
	v_sub_f32_e32 v207, v217, v214
	v_sub_f32_e32 v206, v216, v214
	v_sub_f32_e32 v211, v225, v214
	v_sub_f32_e32 v210, v224, v214
	v_sub_f32_e32 v217, v223, v214
	v_sub_f32_e32 v216, v222, v214
	v_pk_mul_f32 v[206:207], v[214:215], v[206:207] op_sel:[1,0]
	v_pk_mul_f32 v[204:205], v[214:215], v[204:205] op_sel:[1,0]
	v_pk_mul_f32 v[216:217], v[214:215], v[216:217] op_sel:[1,0]
	v_pk_mul_f32 v[210:211], v[214:215], v[210:211] op_sel:[1,0]
	v_sub_f32_e32 v219, v229, v214
	v_sub_f32_e32 v218, v228, v214
	v_sub_f32_e32 v221, v227, v214
	v_sub_f32_e32 v220, v226, v214
	v_pk_fma_f32 v[204:205], v[76:77], v[204:205], v[64:65]
	v_pk_fma_f32 v[206:207], v[78:79], v[206:207], v[66:67]
	v_pk_fma_f32 v[210:211], v[70:71], v[210:211], v[82:83]
	v_pk_fma_f32 v[216:217], v[68:69], v[216:217], v[80:81]
	v_pk_mul_f32 v[220:221], v[214:215], v[220:221] op_sel:[1,0]
	v_pk_mul_f32 v[218:219], v[214:215], v[218:219] op_sel:[1,0]
	v_pk_fma_f32 v[158:159], v[206:207], s[34:35], v[158:159] op_sel_hi:[1,0,1]
	v_pk_fma_f32 v[156:157], v[204:205], s[34:35], v[156:157] op_sel_hi:[1,0,1]
	v_cndmask_b32_e64 v205, v217, v223, s[10:11]
	v_cndmask_b32_e64 v204, v216, v222, s[10:11]
	v_cndmask_b32_e64 v207, v211, v225, s[10:11]
	v_cndmask_b32_e64 v206, v210, v224, s[10:11]
	v_pk_fma_f32 v[218:219], v[74:75], v[218:219], v[86:87]
	v_pk_fma_f32 v[220:221], v[72:73], v[220:221], v[84:85]
	v_pk_fma_f32 v[154:155], v[206:207], s[34:35], v[154:155] op_sel_hi:[1,0,1]
	v_pk_fma_f32 v[152:153], v[204:205], s[34:35], v[152:153] op_sel_hi:[1,0,1]
	v_cndmask_b32_e64 v210, v220, v226, s[10:11]
	v_cndmask_b32_e64 v217, v219, v229, s[10:11]
	v_cvt_pk_bf16_f32 v236, v156, v157
	v_add_f32_e32 v222, v156, v157
	v_mul_f32_e32 v219, v156, v156
	v_mul_f32_e32 v157, v157, v157
	v_cvt_pk_bf16_f32 v238, v152, v153
	v_cvt_pk_bf16_f32 v239, v154, v155
	v_mul_f32_e32 v156, v154, v154
	v_pk_fma_f32 v[204:205], v[154:155], v[154:155], v[156:157] op_sel_hi:[1,1,0]
	v_cndmask_b32_e64 v211, v221, v227, s[10:11]
	v_lshlrev_b32_e32 v165, 16, v213
	v_and_b32_e32 v204, 0xffff0000, v213
	v_cvt_pk_bf16_f32 v237, v158, v159
	v_add_f32_e32 v224, v158, v159
	v_mul_f32_e32 v227, v158, v158
	v_pk_fma_f32 v[206:207], v[210:211], s[34:35], v[148:149] op_sel_hi:[1,0,1]
	v_lshlrev_b32_e32 v156, 16, v212
	v_and_b32_e32 v158, 0xffff0000, v212
	v_sub_f32_e32 v149, v204, v214
	v_sub_f32_e32 v148, v165, v214
	v_sub_f32_e32 v213, v158, v214
	v_sub_f32_e32 v212, v156, v214
	v_pk_mul_f32 v[148:149], v[214:215], v[148:149] op_sel:[1,0]
	v_pk_mul_f32 v[212:213], v[214:215], v[212:213] op_sel:[1,0]
	v_pk_fma_f32 v[148:149], v[90:91], v[148:149], v[94:95]
	v_pk_fma_f32 v[212:213], v[88:89], v[212:213], v[92:93]
	v_cndmask_b32_e64 v149, v149, v204, s[10:11]
	v_cndmask_b32_e64 v148, v148, v165, s[10:11]
	v_mul_f32_e32 v159, v159, v159
	v_cndmask_b32_e64 v216, v218, v228, s[10:11]
	v_cndmask_b32_e64 v213, v213, v158, s[10:11]
	v_cndmask_b32_e64 v212, v212, v156, s[10:11]
	v_pk_fma_f32 v[214:215], v[148:149], s[34:35], v[146:147] op_sel_hi:[1,0,1]
	v_and_b32_e32 v146, 64, v203
	v_mov_b32_e32 v218, v152
	v_mov_b32_e32 v156, v153
	v_mov_b32_e32 v226, v154
	v_mov_b32_e32 v158, v155
	v_mul_f32_e32 v223, v152, v152
	v_mul_f32_e32 v225, v153, v153
	v_pk_fma_f32 v[212:213], v[212:213], s[34:35], v[144:145] op_sel_hi:[1,0,1]
	v_xor_b32_e32 v144, 16, v203
	v_add_u32_e32 v149, 64, v146
	v_pk_add_f32 v[152:153], v[218:219], v[156:157]
	v_pk_add_f32 v[154:155], v[226:227], v[158:159]
	v_pk_fma_f32 v[150:151], v[216:217], s[34:35], v[150:151] op_sel_hi:[1,0,1]
	v_cmp_lt_i32_e32 vcc, v144, v149
	v_pk_add_f32 v[152:153], v[152:153], v[154:155]
	v_pk_add_f32 v[154:155], v[222:223], v[224:225]
	v_mov_b32_e32 v165, v205
	s_nop 1
	v_permlane16_swap_b32_e32 v236, v238
	v_permlane16_swap_b32_e32 v237, v239
	v_lshl_add_u64 v[244:245], v[178:179], 0, v[246:247]
	global_store_dwordx4 v[244:245], v[236:239], off
	v_mul_f32_e32 v217, v206, v206
	v_mul_f32_e32 v221, v207, v207
	v_mul_f32_e32 v229, v150, v150
	v_mul_f32_e32 v231, v151, v151
	v_cndmask_b32_e32 v144, v203, v144, vcc
	v_pk_add_f32 v[154:155], v[154:155], v[164:165]
	v_mov_b32_e32 v216, v206
	v_mov_b32_e32 v220, v207
	v_mov_b32_e32 v228, v150
	v_mov_b32_e32 v230, v151
	v_cvt_pk_bf16_f32 v241, v150, v151
	v_mul_f32_e32 v145, v212, v212
	v_mul_f32_e32 v147, v213, v213
	v_mul_f32_e32 v233, v214, v214
	v_mul_f32_e32 v235, v215, v215
	v_lshlrev_b32_e32 v148, 2, v144
	v_pk_add_f32 v[152:153], v[152:153], v[154:155]
	v_pk_add_f32 v[154:155], v[216:217], v[220:221]
	v_pk_add_f32 v[150:151], v[228:229], v[230:231]
	v_mov_b32_e32 v144, v212
	v_mov_b32_e32 v146, v213
	v_mov_b32_e32 v232, v214
	v_mov_b32_e32 v234, v215
	v_pk_add_f32 v[150:151], v[154:155], v[150:151]
	v_pk_add_f32 v[144:145], v[144:145], v[146:147]
	v_pk_add_f32 v[146:147], v[232:233], v[234:235]
	v_pk_add_f32 v[150:151], v[152:153], v[150:151]
	v_pk_add_f32 v[144:145], v[144:145], v[146:147]
	v_cvt_pk_bf16_f32 v240, v206, v207
	v_pk_add_f32 v[144:145], v[150:151], v[144:145]
	ds_bpermute_b32 v146, v148, v144
	ds_bpermute_b32 v147, v148, v145
	v_xor_b32_e32 v150, 32, v203
	v_cmp_lt_i32_e32 vcc, v150, v149
	v_cvt_pk_bf16_f32 v243, v214, v215
	v_cndmask_b32_e32 v149, v203, v150, vcc
	v_lshlrev_b32_e32 v149, 2, v149
	s_waitcnt lgkmcnt(0)
	v_pk_add_f32 v[144:145], v[144:145], v[146:147]
	ds_bpermute_b32 v146, v149, v144
	ds_bpermute_b32 v147, v149, v145
	v_cvt_pk_bf16_f32 v242, v212, v213
	s_nop 1
	v_permlane16_swap_b32_e32 v240, v242
	v_permlane16_swap_b32_e32 v241, v243
	global_store_dwordx4 v[244:245], v[240:243], off offset:256
	s_and_saveexec_b64 s[50:51], s[8:9]
	s_cbranch_execz .LBB0_1046
	s_waitcnt lgkmcnt(0)
	v_pk_add_f32 v[144:145], v[144:145], v[146:147]
	v_lshlrev_b64 v[146:147], 7, v[176:177]
	v_lshl_add_u64 v[146:147], s[24:25], 0, v[146:147]
	v_lshl_add_u64 v[146:147], s[14:15], 2, v[146:147]
	global_store_dwordx2 v[146:147], v[144:145], off
; #define GASP __attribute__((address_space(1)))
;     __device__ __forceinline__ void operator()(Acc& acc, const Unit& u, int wr, int wc, int fr, int fq, LAS unsigned char* lds) const {
;     ...
;                 const int rl = ai * HALF + wr * 64 + m * 16 + fr, row = u.pm * BM + rl;
;                 const float* rp = (row < split) ? res0 + (size_t)row * D : res1 + (size_t)(row - split) * D;
;                 float* op = out + (size_t)row * D;
;                 f32x2 st = (f32x2){0.f, 1.f}; if (STp) st = SL[rl];
;                 float s = 0.f, q = 0.f;
; #pragma unroll
;                 for (int bj = 0; bj < 2; ++bj)
; #pragma unroll
;                     for (int n = 0; n < 2; ++n) { const int c = col0 + bj * HALF + n * 16; f32x4 r;
;                         if (resb) { const u32x2 w = *(const GASP u32x2*)(resb + (size_t)row * D + c);
;                             r = (f32x4){__uint_as_float(w.x << 16), __uint_as_float(w.x & 0xffff0000u), __uint_as_float(w.y << 16), __uint_as_float(w.y & 0xffff0000u)}; }
;                         else r = *(const GASP f32x4*)(rp + c);
;                         if (STp) r = (r - st[0]) * st[1] * gg[bj][n] + bb[bj][n];
;                         const f32x4 o = r * ALPHA + acc[ai][bj][m][n] * scale;
;                         if (out) *(GASP f32x4*)(op + c) = o;
;                         if (ob) { u32x2 w; w.x = pk2(o[0], o[1]); w.y = pk2(o[2], o[3]); *(GASP u32x2*)(ob + (size_t)row * D + c) = w; }
;                         s += (o[0] + o[1]) + (o[2] + o[3]); q += (o[0] * o[0] + o[1] * o[1]) + (o[2] * o[2] + o[3] * o[3]); }
;                 if (STn) { s += __shfl_xor(s, 16); s += __shfl_xor(s, 32); q += __shfl_xor(q, 16); q += __shfl_xor(q, 32);
;                     if (fq == 0) *(GASP f32x2*)(STn + (size_t)row * 32 + (u.pn * 4 + wc) * 2) = (f32x2){s, q}; }
.LBB0_1046:
	s_or_b64 exec, exec, s[50:51]
	v_add_u32_e32 v144, s37, v185
	v_ashrrev_i32_e32 v145, 31, v144
	v_cmp_gt_i32_e32 vcc, s73, v144
	s_nop 1
	v_cndmask_b32_e32 v145, 0, v145, vcc
	s_waitcnt lgkmcnt(0)
	v_lshlrev_b64 v[146:147], 11, v[144:145]
	v_lshl_add_u64 v[146:147], s[42:43], 0, v[146:147]
	v_lshl_add_u64 v[146:147], v[174:175], 1, v[146:147]
	global_load_dwordx2 v[150:151], v[146:147], off
	global_load_dwordx2 v[152:153], v[146:147], off offset:32
	global_load_dwordx2 v[154:155], v[146:147], off offset:256
	global_load_dwordx2 v[156:157], v[146:147], off offset:288
	ds_read_b64 v[158:159], v186
	s_waitcnt vmcnt(3)
	v_lshlrev_b32_e32 v176, 16, v151
	v_and_b32_e32 v177, 0xffff0000, v151
	s_waitcnt vmcnt(2)
	v_lshlrev_b32_e32 v212, 16, v153
	v_and_b32_e32 v213, 0xffff0000, v153
	v_lshlrev_b32_e32 v165, 16, v150
	v_and_b32_e32 v150, 0xffff0000, v150
	v_lshlrev_b32_e32 v210, 16, v152
	v_and_b32_e32 v211, 0xffff0000, v152
	s_waitcnt vmcnt(1)
	v_lshlrev_b32_e32 v214, 16, v154
	v_and_b32_e32 v215, 0xffff0000, v154
	v_lshlrev_b32_e32 v216, 16, v155
	v_and_b32_e32 v217, 0xffff0000, v155
	s_waitcnt lgkmcnt(0)
	v_sub_f32_e32 v153, v177, v158
	v_sub_f32_e32 v152, v176, v158
	v_sub_f32_e32 v155, v213, v158
	v_sub_f32_e32 v154, v212, v158
	s_waitcnt vmcnt(0)
	v_lshlrev_b32_e32 v218, 16, v156
	v_and_b32_e32 v219, 0xffff0000, v156
	v_lshlrev_b32_e32 v220, 16, v157
	v_and_b32_e32 v221, 0xffff0000, v157
	v_sub_f32_e32 v151, v150, v158
	v_sub_f32_e32 v150, v165, v158
	v_sub_f32_e32 v157, v211, v158
	v_sub_f32_e32 v156, v210, v158
	v_pk_mul_f32 v[152:153], v[158:159], v[152:153] op_sel:[1,0]
	v_pk_mul_f32 v[154:155], v[158:159], v[154:155] op_sel:[1,0]
	v_sub_f32_e32 v177, v217, v158
	v_sub_f32_e32 v176, v216, v158
	v_sub_f32_e32 v179, v215, v158
	v_sub_f32_e32 v178, v214, v158
	v_sub_f32_e32 v207, v219, v158
	v_sub_f32_e32 v206, v218, v158
	v_pk_mul_f32 v[150:151], v[158:159], v[150:151] op_sel:[1,0]
	v_pk_mul_f32 v[156:157], v[158:159], v[156:157] op_sel:[1,0]
	v_pk_fma_f32 v[152:153], v[78:79], v[152:153], v[66:67]
	v_pk_fma_f32 v[154:155], v[70:71], v[154:155], v[82:83]
	v_sub_f32_e32 v205, v221, v158
	v_sub_f32_e32 v204, v220, v158
	v_pk_mul_f32 v[178:179], v[158:159], v[178:179] op_sel:[1,0]
	v_pk_mul_f32 v[176:177], v[158:159], v[176:177] op_sel:[1,0]
	v_pk_mul_f32 v[206:207], v[158:159], v[206:207] op_sel:[1,0]
	v_pk_fma_f32 v[150:151], v[76:77], v[150:151], v[64:65]
	v_pk_fma_f32 v[156:157], v[68:69], v[156:157], v[80:81]
	v_pk_fma_f32 v[142:143], v[152:153], s[34:35], v[142:143] op_sel_hi:[1,0,1]
	v_cndmask_b32_e64 v153, v155, v213, s[10:11]
	v_cndmask_b32_e64 v152, v154, v212, s[10:11]
	v_pk_mul_f32 v[158:159], v[158:159], v[204:205] op_sel:[1,0]
	v_pk_fma_f32 v[176:177], v[74:75], v[176:177], v[86:87]
	v_pk_fma_f32 v[178:179], v[72:73], v[178:179], v[84:85]
	v_pk_fma_f32 v[204:205], v[88:89], v[206:207], v[92:93]
	v_pk_fma_f32 v[140:141], v[150:151], s[34:35], v[140:141] op_sel_hi:[1,0,1]
	v_cndmask_b32_e64 v151, v157, v211, s[10:11]
	v_cndmask_b32_e64 v150, v156, v210, s[10:11]
	v_pk_fma_f32 v[138:139], v[152:153], s[34:35], v[138:139] op_sel_hi:[1,0,1]
	v_cndmask_b32_e64 v154, v178, v214, s[10:11]
	v_cndmask_b32_e64 v156, v176, v216, s[10:11]
	v_cndmask_b32_e64 v176, v204, v218, s[10:11]
	v_cvt_pk_bf16_f32 v236, v140, v141
	v_add_f32_e32 v204, v140, v141
	v_mul_f32_e32 v211, v140, v140
	v_mul_f32_e32 v141, v141, v141
	v_pk_fma_f32 v[136:137], v[150:151], s[34:35], v[136:137] op_sel_hi:[1,0,1]
	v_mul_f32_e32 v140, v138, v138
	v_cndmask_b32_e64 v155, v179, v215, s[10:11]
	v_cvt_pk_bf16_f32 v237, v142, v143
	v_add_f32_e32 v206, v142, v143
	v_mul_f32_e32 v213, v142, v142
	v_mul_f32_e32 v143, v143, v143
	v_pk_fma_f32 v[214:215], v[138:139], v[138:139], v[140:141] op_sel_hi:[1,1,0]
	v_mov_b32_e32 v210, v136
	v_mov_b32_e32 v140, v137
	v_mov_b32_e32 v212, v138
	v_mov_b32_e32 v142, v139
	v_pk_fma_f32 v[158:159], v[90:91], v[158:159], v[94:95]
	v_cndmask_b32_e64 v157, v177, v217, s[10:11]
	v_cndmask_b32_e64 v177, v205, v219, s[10:11]
	v_cvt_pk_bf16_f32 v238, v136, v137
	v_mul_f32_e32 v205, v136, v136
	v_mul_f32_e32 v207, v137, v137
	v_pk_add_f32 v[136:137], v[210:211], v[140:141]
	v_pk_add_f32 v[140:141], v[212:213], v[142:143]
	v_pk_fma_f32 v[134:135], v[156:157], s[34:35], v[134:135] op_sel_hi:[1,0,1]
	v_pk_fma_f32 v[132:133], v[154:155], s[34:35], v[132:133] op_sel_hi:[1,0,1]
	v_cndmask_b32_e64 v159, v159, v221, s[10:11]
	v_cndmask_b32_e64 v158, v158, v220, s[10:11]
	v_pk_add_f32 v[136:137], v[136:137], v[140:141]
	v_pk_add_f32 v[140:141], v[204:205], v[206:207]
	v_mov_b32_e32 v165, v215
	v_mul_f32_e32 v153, v132, v132
	v_mul_f32_e32 v155, v133, v133
	v_mul_f32_e32 v157, v134, v134
	v_mul_f32_e32 v179, v135, v135
	v_pk_fma_f32 v[158:159], v[158:159], s[34:35], v[130:131] op_sel_hi:[1,0,1]
	v_pk_fma_f32 v[176:177], v[176:177], s[34:35], v[128:129] op_sel_hi:[1,0,1]
	v_pk_add_f32 v[140:141], v[140:141], v[164:165]
	v_mov_b32_e32 v152, v132
	v_mov_b32_e32 v154, v133
	v_mov_b32_e32 v156, v134
	v_mov_b32_e32 v178, v135
	v_mul_f32_e32 v129, v176, v176
	v_mul_f32_e32 v131, v177, v177
	v_mul_f32_e32 v217, v158, v158
	v_mul_f32_e32 v219, v159, v159
	v_pk_add_f32 v[136:137], v[136:137], v[140:141]
	v_pk_add_f32 v[140:141], v[152:153], v[154:155]
	v_pk_add_f32 v[142:143], v[156:157], v[178:179]
	v_mov_b32_e32 v128, v176
	v_mov_b32_e32 v130, v177
	v_mov_b32_e32 v216, v158
	v_mov_b32_e32 v218, v159
	v_pk_add_f32 v[140:141], v[140:141], v[142:143]
	v_pk_add_f32 v[128:129], v[128:129], v[130:131]
	v_pk_add_f32 v[130:131], v[216:217], v[218:219]
	v_pk_add_f32 v[136:137], v[136:137], v[140:141]
	v_pk_add_f32 v[128:129], v[128:129], v[130:131]
	v_cvt_pk_bf16_f32 v240, v132, v133
	v_pk_add_f32 v[128:129], v[136:137], v[128:129]
	ds_bpermute_b32 v130, v148, v128
	ds_bpermute_b32 v131, v148, v129
	v_cvt_pk_bf16_f32 v241, v134, v135
	v_cvt_pk_bf16_f32 v239, v138, v139
	v_cvt_pk_bf16_f32 v242, v176, v177
	s_waitcnt lgkmcnt(0)
	v_pk_add_f32 v[128:129], v[128:129], v[130:131]
	ds_bpermute_b32 v130, v149, v128
	ds_bpermute_b32 v131, v149, v129
	v_cvt_pk_bf16_f32 v243, v158, v159
	s_nop 1
	v_permlane16_swap_b32_e32 v236, v238
	v_permlane16_swap_b32_e32 v237, v239
	v_lshl_add_u64 v[244:245], v[146:147], 0, v[246:247]
	global_store_dwordx4 v[244:245], v[236:239], off
	s_nop 1
	v_permlane16_swap_b32_e32 v240, v242
	v_permlane16_swap_b32_e32 v241, v243
	global_store_dwordx4 v[244:245], v[240:243], off offset:256
	s_and_saveexec_b64 s[50:51], s[8:9]
	s_cbranch_execz .LBB0_1048
	s_waitcnt lgkmcnt(0)
	v_pk_add_f32 v[128:129], v[128:129], v[130:131]
	v_lshlrev_b64 v[130:131], 7, v[144:145]
	v_lshl_add_u64 v[130:131], s[24:25], 0, v[130:131]
	v_lshl_add_u64 v[130:131], s[14:15], 2, v[130:131]
	global_store_dwordx2 v[130:131], v[128:129], off
; #define GASP __attribute__((address_space(1)))
;     __device__ __forceinline__ void operator()(Acc& acc, const Unit& u, int wr, int wc, int fr, int fq, LAS unsigned char* lds) const {
;     ...
;                 const int rl = ai * HALF + wr * 64 + m * 16 + fr, row = u.pm * BM + rl;
;                 const float* rp = (row < split) ? res0 + (size_t)row * D : res1 + (size_t)(row - split) * D;
;                 float* op = out + (size_t)row * D;
;                 f32x2 st = (f32x2){0.f, 1.f}; if (STp) st = SL[rl];
;                 float s = 0.f, q = 0.f;
; #pragma unroll
;                 for (int bj = 0; bj < 2; ++bj)
; #pragma unroll
;                     for (int n = 0; n < 2; ++n) { const int c = col0 + bj * HALF + n * 16; f32x4 r;
;                         if (resb) { const u32x2 w = *(const GASP u32x2*)(resb + (size_t)row * D + c);
;                             r = (f32x4){__uint_as_float(w.x << 16), __uint_as_float(w.x & 0xffff0000u), __uint_as_float(w.y << 16), __uint_as_float(w.y & 0xffff0000u)}; }
;                         else r = *(const GASP f32x4*)(rp + c);
;                         if (STp) r = (r - st[0]) * st[1] * gg[bj][n] + bb[bj][n];
;                         const f32x4 o = r * ALPHA + acc[ai][bj][m][n] * scale;
;                         if (out) *(GASP f32x4*)(op + c) = o;
;                         if (ob) { u32x2 w; w.x = pk2(o[0], o[1]); w.y = pk2(o[2], o[3]); *(GASP u32x2*)(ob + (size_t)row * D + c) = w; }
;                         s += (o[0] + o[1]) + (o[2] + o[3]); q += (o[0] * o[0] + o[1] * o[1]) + (o[2] * o[2] + o[3] * o[3]); }
;                 if (STn) { s += __shfl_xor(s, 16); s += __shfl_xor(s, 32); q += __shfl_xor(q, 16); q += __shfl_xor(q, 32);
;                     if (fq == 0) *(GASP f32x2*)(STn + (size_t)row * 32 + (u.pn * 4 + wc) * 2) = (f32x2){s, q}; }
.LBB0_1048:
	s_or_b64 exec, exec, s[50:51]
	v_add_u32_e32 v128, s37, v187
	v_ashrrev_i32_e32 v129, 31, v128
	v_cmp_gt_i32_e32 vcc, s73, v128
	s_nop 1
	v_cndmask_b32_e32 v129, 0, v129, vcc
	s_waitcnt lgkmcnt(0)
	v_lshlrev_b64 v[130:131], 11, v[128:129]
	v_lshl_add_u64 v[130:131], s[42:43], 0, v[130:131]
	v_lshl_add_u64 v[130:131], v[174:175], 1, v[130:131]
	global_load_dwordx2 v[132:133], v[130:131], off
	global_load_dwordx2 v[134:135], v[130:131], off offset:32
	global_load_dwordx2 v[136:137], v[130:131], off offset:256
	global_load_dwordx2 v[138:139], v[130:131], off offset:288
	ds_read_b64 v[140:141], v188
	s_waitcnt vmcnt(3)
	v_lshlrev_b32_e32 v143, 16, v133
	v_and_b32_e32 v144, 0xffff0000, v133
	s_waitcnt vmcnt(2)
	v_lshlrev_b32_e32 v154, 16, v135
	v_and_b32_e32 v155, 0xffff0000, v135
	v_lshlrev_b32_e32 v142, 16, v132
	v_and_b32_e32 v132, 0xffff0000, v132
	v_lshlrev_b32_e32 v152, 16, v134
	v_and_b32_e32 v153, 0xffff0000, v134
	s_waitcnt vmcnt(1)
	v_lshlrev_b32_e32 v156, 16, v136
	v_and_b32_e32 v157, 0xffff0000, v136
	v_lshlrev_b32_e32 v158, 16, v137
	v_and_b32_e32 v159, 0xffff0000, v137
	s_waitcnt lgkmcnt(0)
	v_sub_f32_e32 v135, v144, v140
	v_sub_f32_e32 v134, v143, v140
	v_sub_f32_e32 v137, v155, v140
	v_sub_f32_e32 v136, v154, v140
	s_waitcnt vmcnt(0)
	v_lshlrev_b32_e32 v165, 16, v138
	v_and_b32_e32 v176, 0xffff0000, v138
	v_lshlrev_b32_e32 v177, 16, v139
	v_and_b32_e32 v178, 0xffff0000, v139
	v_sub_f32_e32 v133, v132, v140
	v_sub_f32_e32 v132, v142, v140
	v_sub_f32_e32 v139, v153, v140
	v_sub_f32_e32 v138, v152, v140
	v_pk_mul_f32 v[134:135], v[140:141], v[134:135] op_sel:[1,0]
	v_pk_mul_f32 v[136:137], v[140:141], v[136:137] op_sel:[1,0]
	v_sub_f32_e32 v143, v159, v140
	v_sub_f32_e32 v142, v158, v140
	v_sub_f32_e32 v145, v157, v140
	v_sub_f32_e32 v144, v156, v140
	v_sub_f32_e32 v151, v176, v140
	v_sub_f32_e32 v150, v165, v140
	v_pk_mul_f32 v[132:133], v[140:141], v[132:133] op_sel:[1,0]
	v_pk_mul_f32 v[138:139], v[140:141], v[138:139] op_sel:[1,0]
	v_pk_fma_f32 v[134:135], v[78:79], v[134:135], v[66:67]
	v_pk_fma_f32 v[136:137], v[70:71], v[136:137], v[82:83]
	v_sub_f32_e32 v147, v178, v140
	v_sub_f32_e32 v146, v177, v140
	v_pk_mul_f32 v[144:145], v[140:141], v[144:145] op_sel:[1,0]
	v_pk_mul_f32 v[142:143], v[140:141], v[142:143] op_sel:[1,0]
	v_pk_mul_f32 v[150:151], v[140:141], v[150:151] op_sel:[1,0]
	v_pk_fma_f32 v[132:133], v[76:77], v[132:133], v[64:65]
	v_pk_fma_f32 v[138:139], v[68:69], v[138:139], v[80:81]
	v_pk_fma_f32 v[126:127], v[134:135], s[34:35], v[126:127] op_sel_hi:[1,0,1]
	v_cndmask_b32_e64 v135, v137, v155, s[10:11]
	v_cndmask_b32_e64 v134, v136, v154, s[10:11]
	v_pk_mul_f32 v[140:141], v[140:141], v[146:147] op_sel:[1,0]
	v_pk_fma_f32 v[142:143], v[74:75], v[142:143], v[86:87]
	v_pk_fma_f32 v[144:145], v[72:73], v[144:145], v[84:85]
	v_pk_fma_f32 v[146:147], v[88:89], v[150:151], v[92:93]
	v_pk_fma_f32 v[124:125], v[132:133], s[34:35], v[124:125] op_sel_hi:[1,0,1]
	v_cndmask_b32_e64 v133, v139, v153, s[10:11]
	v_cndmask_b32_e64 v132, v138, v152, s[10:11]
	v_pk_fma_f32 v[122:123], v[134:135], s[34:35], v[122:123] op_sel_hi:[1,0,1]
	v_cndmask_b32_e64 v136, v144, v156, s[10:11]
	v_cndmask_b32_e64 v138, v142, v158, s[10:11]
	v_cndmask_b32_e64 v142, v146, v165, s[10:11]
	v_cvt_pk_bf16_f32 v236, v124, v125
	v_add_f32_e32 v146, v124, v125
	v_mul_f32_e32 v153, v124, v124
	v_mul_f32_e32 v125, v125, v125
	v_pk_fma_f32 v[120:121], v[132:133], s[34:35], v[120:121] op_sel_hi:[1,0,1]
	v_mul_f32_e32 v124, v122, v122
	v_cndmask_b32_e64 v137, v145, v157, s[10:11]
	v_cvt_pk_bf16_f32 v237, v126, v127
	v_add_f32_e32 v150, v126, v127
	v_mul_f32_e32 v155, v126, v126
	v_mul_f32_e32 v127, v127, v127
	v_pk_fma_f32 v[156:157], v[122:123], v[122:123], v[124:125] op_sel_hi:[1,1,0]
	v_mov_b32_e32 v152, v120
	v_mov_b32_e32 v124, v121
	v_mov_b32_e32 v154, v122
	v_mov_b32_e32 v126, v123
	v_pk_fma_f32 v[140:141], v[90:91], v[140:141], v[94:95]
	v_cndmask_b32_e64 v139, v143, v159, s[10:11]
	v_cndmask_b32_e64 v143, v147, v176, s[10:11]
	v_cvt_pk_bf16_f32 v238, v120, v121
	v_mul_f32_e32 v147, v120, v120
	v_mul_f32_e32 v151, v121, v121
	v_pk_add_f32 v[120:121], v[152:153], v[124:125]
	v_pk_add_f32 v[124:125], v[154:155], v[126:127]
	v_pk_fma_f32 v[118:119], v[138:139], s[34:35], v[118:119] op_sel_hi:[1,0,1]
	v_pk_fma_f32 v[116:117], v[136:137], s[34:35], v[116:117] op_sel_hi:[1,0,1]
	v_cndmask_b32_e64 v141, v141, v178, s[10:11]
	v_cndmask_b32_e64 v140, v140, v177, s[10:11]
	v_pk_add_f32 v[120:121], v[120:121], v[124:125]
	v_pk_add_f32 v[124:125], v[146:147], v[150:151]
	v_mov_b32_e32 v165, v157
	v_mul_f32_e32 v135, v116, v116
	v_mul_f32_e32 v137, v117, v117
	v_mul_f32_e32 v139, v118, v118
	v_mul_f32_e32 v145, v119, v119
	v_pk_fma_f32 v[140:141], v[140:141], s[34:35], v[114:115] op_sel_hi:[1,0,1]
	v_pk_fma_f32 v[142:143], v[142:143], s[34:35], v[112:113] op_sel_hi:[1,0,1]
	v_pk_add_f32 v[124:125], v[124:125], v[164:165]
	v_mov_b32_e32 v134, v116
	v_mov_b32_e32 v136, v117
	v_mov_b32_e32 v138, v118
	v_mov_b32_e32 v144, v119
	v_mul_f32_e32 v113, v142, v142
	v_mul_f32_e32 v115, v143, v143
	v_mul_f32_e32 v159, v140, v140
	v_mul_f32_e32 v177, v141, v141
	v_pk_add_f32 v[120:121], v[120:121], v[124:125]
	v_pk_add_f32 v[124:125], v[134:135], v[136:137]
	v_pk_add_f32 v[126:127], v[138:139], v[144:145]
	v_mov_b32_e32 v112, v142
	v_mov_b32_e32 v114, v143
	v_mov_b32_e32 v158, v140
	v_mov_b32_e32 v176, v141
	v_pk_add_f32 v[124:125], v[124:125], v[126:127]
	v_pk_add_f32 v[112:113], v[112:113], v[114:115]
	v_pk_add_f32 v[114:115], v[158:159], v[176:177]
	v_pk_add_f32 v[120:121], v[120:121], v[124:125]
	v_pk_add_f32 v[112:113], v[112:113], v[114:115]
	v_cvt_pk_bf16_f32 v240, v116, v117
	v_pk_add_f32 v[112:113], v[120:121], v[112:113]
	ds_bpermute_b32 v114, v148, v112
	ds_bpermute_b32 v115, v148, v113
	v_cvt_pk_bf16_f32 v241, v118, v119
	v_cvt_pk_bf16_f32 v239, v122, v123
	v_cvt_pk_bf16_f32 v242, v142, v143
	s_waitcnt lgkmcnt(0)
	v_pk_add_f32 v[112:113], v[112:113], v[114:115]
	ds_bpermute_b32 v114, v149, v112
	ds_bpermute_b32 v115, v149, v113
	v_cvt_pk_bf16_f32 v243, v140, v141
	s_nop 1
	v_permlane16_swap_b32_e32 v236, v238
	v_permlane16_swap_b32_e32 v237, v239
	v_lshl_add_u64 v[244:245], v[130:131], 0, v[246:247]
	global_store_dwordx4 v[244:245], v[236:239], off
	s_nop 1
	v_permlane16_swap_b32_e32 v240, v242
	v_permlane16_swap_b32_e32 v241, v243
	global_store_dwordx4 v[244:245], v[240:243], off offset:256
	s_and_saveexec_b64 s[50:51], s[8:9]
	s_cbranch_execz .LBB0_1050
	s_waitcnt lgkmcnt(0)
	v_pk_add_f32 v[112:113], v[112:113], v[114:115]
	v_lshlrev_b64 v[114:115], 7, v[128:129]
	v_lshl_add_u64 v[114:115], s[24:25], 0, v[114:115]
	v_lshl_add_u64 v[114:115], s[14:15], 2, v[114:115]
	global_store_dwordx2 v[114:115], v[112:113], off
; #define GASP __attribute__((address_space(1)))
;     __device__ __forceinline__ void operator()(Acc& acc, const Unit& u, int wr, int wc, int fr, int fq, LAS unsigned char* lds) const {
;     ...
;                 const int rl = ai * HALF + wr * 64 + m * 16 + fr, row = u.pm * BM + rl;
;                 const float* rp = (row < split) ? res0 + (size_t)row * D : res1 + (size_t)(row - split) * D;
;                 float* op = out + (size_t)row * D;
;                 f32x2 st = (f32x2){0.f, 1.f}; if (STp) st = SL[rl];
;                 float s = 0.f, q = 0.f;
; #pragma unroll
;                 for (int bj = 0; bj < 2; ++bj)
; #pragma unroll
;                     for (int n = 0; n < 2; ++n) { const int c = col0 + bj * HALF + n * 16; f32x4 r;
;                         if (resb) { const u32x2 w = *(const GASP u32x2*)(resb + (size_t)row * D + c);
;                             r = (f32x4){__uint_as_float(w.x << 16), __uint_as_float(w.x & 0xffff0000u), __uint_as_float(w.y << 16), __uint_as_float(w.y & 0xffff0000u)}; }
;                         else r = *(const GASP f32x4*)(rp + c);
;                         if (STp) r = (r - st[0]) * st[1] * gg[bj][n] + bb[bj][n];
;                         const f32x4 o = r * ALPHA + acc[ai][bj][m][n] * scale;
;                         if (out) *(GASP f32x4*)(op + c) = o;
;                         if (ob) { u32x2 w; w.x = pk2(o[0], o[1]); w.y = pk2(o[2], o[3]); *(GASP u32x2*)(ob + (size_t)row * D + c) = w; }
;                         s += (o[0] + o[1]) + (o[2] + o[3]); q += (o[0] * o[0] + o[1] * o[1]) + (o[2] * o[2] + o[3] * o[3]); }
;                 if (STn) { s += __shfl_xor(s, 16); s += __shfl_xor(s, 32); q += __shfl_xor(q, 16); q += __shfl_xor(q, 32);
;                     if (fq == 0) *(GASP f32x2*)(STn + (size_t)row * 32 + (u.pn * 4 + wc) * 2) = (f32x2){s, q}; }
.LBB0_1050:
	s_or_b64 exec, exec, s[50:51]
	v_add_u32_e32 v112, s37, v189
	v_ashrrev_i32_e32 v113, 31, v112
	v_cmp_gt_i32_e32 vcc, s73, v112
	s_nop 1
	v_cndmask_b32_e32 v113, 0, v113, vcc
	s_waitcnt lgkmcnt(0)
	v_lshlrev_b64 v[114:115], 11, v[112:113]
	v_lshl_add_u64 v[114:115], s[42:43], 0, v[114:115]
	v_lshl_add_u64 v[114:115], v[174:175], 1, v[114:115]
	global_load_dwordx2 v[116:117], v[114:115], off
	global_load_dwordx2 v[118:119], v[114:115], off offset:32
	global_load_dwordx2 v[120:121], v[114:115], off offset:256
	global_load_dwordx2 v[122:123], v[114:115], off offset:288
	ds_read_b64 v[124:125], v190
	s_waitcnt vmcnt(3)
	v_lshlrev_b32_e32 v127, 16, v117
	v_and_b32_e32 v128, 0xffff0000, v117
	s_waitcnt vmcnt(2)
	v_lshlrev_b32_e32 v136, 16, v119
	v_and_b32_e32 v137, 0xffff0000, v119
	v_lshlrev_b32_e32 v126, 16, v116
	v_and_b32_e32 v116, 0xffff0000, v116
	v_lshlrev_b32_e32 v134, 16, v118
	v_and_b32_e32 v135, 0xffff0000, v118
	s_waitcnt vmcnt(1)
	v_lshlrev_b32_e32 v138, 16, v120
	v_and_b32_e32 v139, 0xffff0000, v120
	v_lshlrev_b32_e32 v140, 16, v121
	v_and_b32_e32 v141, 0xffff0000, v121
	s_waitcnt lgkmcnt(0)
	v_sub_f32_e32 v119, v128, v124
	v_sub_f32_e32 v118, v127, v124
	v_sub_f32_e32 v121, v137, v124
	v_sub_f32_e32 v120, v136, v124
	s_waitcnt vmcnt(0)
	v_lshlrev_b32_e32 v142, 16, v122
	v_and_b32_e32 v143, 0xffff0000, v122
	v_lshlrev_b32_e32 v144, 16, v123
	v_and_b32_e32 v145, 0xffff0000, v123
	v_sub_f32_e32 v117, v116, v124
	v_sub_f32_e32 v116, v126, v124
	v_sub_f32_e32 v123, v135, v124
	v_sub_f32_e32 v122, v134, v124
	v_pk_mul_f32 v[118:119], v[124:125], v[118:119] op_sel:[1,0]
	v_pk_mul_f32 v[120:121], v[124:125], v[120:121] op_sel:[1,0]
	v_sub_f32_e32 v127, v141, v124
	v_sub_f32_e32 v126, v140, v124
	v_sub_f32_e32 v129, v139, v124
	v_sub_f32_e32 v128, v138, v124
	v_sub_f32_e32 v133, v143, v124
	v_sub_f32_e32 v132, v142, v124
	v_pk_mul_f32 v[116:117], v[124:125], v[116:117] op_sel:[1,0]
	v_pk_mul_f32 v[122:123], v[124:125], v[122:123] op_sel:[1,0]
	v_pk_fma_f32 v[118:119], v[78:79], v[118:119], v[66:67]
	v_pk_fma_f32 v[120:121], v[70:71], v[120:121], v[82:83]
	v_sub_f32_e32 v131, v145, v124
	v_sub_f32_e32 v130, v144, v124
	v_pk_mul_f32 v[128:129], v[124:125], v[128:129] op_sel:[1,0]
	v_pk_mul_f32 v[126:127], v[124:125], v[126:127] op_sel:[1,0]
	v_pk_mul_f32 v[132:133], v[124:125], v[132:133] op_sel:[1,0]
	v_pk_fma_f32 v[116:117], v[76:77], v[116:117], v[64:65]
	v_pk_fma_f32 v[122:123], v[68:69], v[122:123], v[80:81]
	v_pk_fma_f32 v[110:111], v[118:119], s[34:35], v[110:111] op_sel_hi:[1,0,1]
	v_cndmask_b32_e64 v119, v121, v137, s[10:11]
	v_cndmask_b32_e64 v118, v120, v136, s[10:11]
	v_pk_mul_f32 v[124:125], v[124:125], v[130:131] op_sel:[1,0]
	v_pk_fma_f32 v[126:127], v[74:75], v[126:127], v[86:87]
	v_pk_fma_f32 v[128:129], v[72:73], v[128:129], v[84:85]
	v_pk_fma_f32 v[130:131], v[88:89], v[132:133], v[92:93]
	v_pk_fma_f32 v[108:109], v[116:117], s[34:35], v[108:109] op_sel_hi:[1,0,1]
	v_cndmask_b32_e64 v117, v123, v135, s[10:11]
	v_cndmask_b32_e64 v116, v122, v134, s[10:11]
	v_pk_fma_f32 v[106:107], v[118:119], s[34:35], v[106:107] op_sel_hi:[1,0,1]
	v_cndmask_b32_e64 v120, v128, v138, s[10:11]
	v_cndmask_b32_e64 v122, v126, v140, s[10:11]
	v_cndmask_b32_e64 v126, v130, v142, s[10:11]
	v_cvt_pk_bf16_f32 v236, v108, v109
	v_add_f32_e32 v130, v108, v109
	v_mul_f32_e32 v135, v108, v108
	v_mul_f32_e32 v109, v109, v109
	v_pk_fma_f32 v[104:105], v[116:117], s[34:35], v[104:105] op_sel_hi:[1,0,1]
	v_mul_f32_e32 v108, v106, v106
	v_cndmask_b32_e64 v121, v129, v139, s[10:11]
	v_cvt_pk_bf16_f32 v237, v110, v111
	v_add_f32_e32 v132, v110, v111
	v_mul_f32_e32 v137, v110, v110
	v_mul_f32_e32 v111, v111, v111
	v_pk_fma_f32 v[138:139], v[106:107], v[106:107], v[108:109] op_sel_hi:[1,1,0]
	v_mov_b32_e32 v134, v104
	v_mov_b32_e32 v108, v105
	v_mov_b32_e32 v136, v106
	v_mov_b32_e32 v110, v107
	v_pk_fma_f32 v[124:125], v[90:91], v[124:125], v[94:95]
	v_cndmask_b32_e64 v123, v127, v141, s[10:11]
	v_cndmask_b32_e64 v127, v131, v143, s[10:11]
	v_cvt_pk_bf16_f32 v238, v104, v105
	v_mul_f32_e32 v131, v104, v104
	v_mul_f32_e32 v133, v105, v105
	v_pk_add_f32 v[104:105], v[134:135], v[108:109]
	v_pk_add_f32 v[108:109], v[136:137], v[110:111]
	v_pk_fma_f32 v[102:103], v[122:123], s[34:35], v[102:103] op_sel_hi:[1,0,1]
	v_pk_fma_f32 v[100:101], v[120:121], s[34:35], v[100:101] op_sel_hi:[1,0,1]
	v_cndmask_b32_e64 v125, v125, v145, s[10:11]
	v_cndmask_b32_e64 v124, v124, v144, s[10:11]
	v_pk_add_f32 v[104:105], v[104:105], v[108:109]
	v_pk_add_f32 v[108:109], v[130:131], v[132:133]
	v_mov_b32_e32 v165, v139
	v_mul_f32_e32 v119, v100, v100
	v_mul_f32_e32 v121, v101, v101
	v_mul_f32_e32 v123, v102, v102
	v_mul_f32_e32 v129, v103, v103
	v_pk_fma_f32 v[124:125], v[124:125], s[34:35], v[98:99] op_sel_hi:[1,0,1]
	v_pk_fma_f32 v[126:127], v[126:127], s[34:35], v[96:97] op_sel_hi:[1,0,1]
	v_pk_add_f32 v[108:109], v[108:109], v[164:165]
	v_mov_b32_e32 v118, v100
	v_mov_b32_e32 v120, v101
	v_mov_b32_e32 v122, v102
	v_mov_b32_e32 v128, v103
	v_mul_f32_e32 v97, v126, v126
	v_mul_f32_e32 v99, v127, v127
	v_mul_f32_e32 v141, v124, v124
	v_mul_f32_e32 v143, v125, v125
	v_pk_add_f32 v[104:105], v[104:105], v[108:109]
	v_pk_add_f32 v[108:109], v[118:119], v[120:121]
	v_pk_add_f32 v[110:111], v[122:123], v[128:129]
	v_mov_b32_e32 v96, v126
	v_mov_b32_e32 v98, v127
	v_mov_b32_e32 v140, v124
	v_mov_b32_e32 v142, v125
	v_pk_add_f32 v[108:109], v[108:109], v[110:111]
	v_pk_add_f32 v[96:97], v[96:97], v[98:99]
	v_pk_add_f32 v[98:99], v[140:141], v[142:143]
	v_pk_add_f32 v[104:105], v[104:105], v[108:109]
	v_pk_add_f32 v[96:97], v[96:97], v[98:99]
	v_cvt_pk_bf16_f32 v240, v100, v101
	v_pk_add_f32 v[96:97], v[104:105], v[96:97]
	ds_bpermute_b32 v98, v148, v96
	ds_bpermute_b32 v99, v148, v97
	v_cvt_pk_bf16_f32 v241, v102, v103
	v_cvt_pk_bf16_f32 v239, v106, v107
	v_cvt_pk_bf16_f32 v242, v126, v127
	s_waitcnt lgkmcnt(0)
	v_pk_add_f32 v[96:97], v[96:97], v[98:99]
	ds_bpermute_b32 v98, v149, v96
	ds_bpermute_b32 v99, v149, v97
	v_cvt_pk_bf16_f32 v243, v124, v125
	s_nop 1
	v_permlane16_swap_b32_e32 v236, v238
	v_permlane16_swap_b32_e32 v237, v239
	v_lshl_add_u64 v[244:245], v[114:115], 0, v[246:247]
	global_store_dwordx4 v[244:245], v[236:239], off
	s_nop 1
	v_permlane16_swap_b32_e32 v240, v242
	v_permlane16_swap_b32_e32 v241, v243
	global_store_dwordx4 v[244:245], v[240:243], off offset:256
	s_and_saveexec_b64 s[50:51], s[8:9]
	s_cbranch_execz .LBB0_1052
	s_waitcnt lgkmcnt(0)
	v_pk_add_f32 v[96:97], v[96:97], v[98:99]
	v_lshlrev_b64 v[98:99], 7, v[112:113]
	v_lshl_add_u64 v[98:99], s[24:25], 0, v[98:99]
	v_lshl_add_u64 v[98:99], s[14:15], 2, v[98:99]
	global_store_dwordx2 v[98:99], v[96:97], off
; #define GASP __attribute__((address_space(1)))
;     __device__ __forceinline__ void operator()(Acc& acc, const Unit& u, int wr, int wc, int fr, int fq, LAS unsigned char* lds) const {
;     ...
;                 const int rl = ai * HALF + wr * 64 + m * 16 + fr, row = u.pm * BM + rl;
;                 const float* rp = (row < split) ? res0 + (size_t)row * D : res1 + (size_t)(row - split) * D;
;                 float* op = out + (size_t)row * D;
;                 f32x2 st = (f32x2){0.f, 1.f}; if (STp) st = SL[rl];
;                 float s = 0.f, q = 0.f;
; #pragma unroll
;                 for (int bj = 0; bj < 2; ++bj)
; #pragma unroll
;                     for (int n = 0; n < 2; ++n) { const int c = col0 + bj * HALF + n * 16; f32x4 r;
;                         if (resb) { const u32x2 w = *(const GASP u32x2*)(resb + (size_t)row * D + c);
;                             r = (f32x4){__uint_as_float(w.x << 16), __uint_as_float(w.x & 0xffff0000u), __uint_as_float(w.y << 16), __uint_as_float(w.y & 0xffff0000u)}; }
;                         else r = *(const GASP f32x4*)(rp + c);
;                         if (STp) r = (r - st[0]) * st[1] * gg[bj][n] + bb[bj][n];
;                         const f32x4 o = r * ALPHA + acc[ai][bj][m][n] * scale;
;                         if (out) *(GASP f32x4*)(op + c) = o;
;                         if (ob) { u32x2 w; w.x = pk2(o[0], o[1]); w.y = pk2(o[2], o[3]); *(GASP u32x2*)(ob + (size_t)row * D + c) = w; }
;                         s += (o[0] + o[1]) + (o[2] + o[3]); q += (o[0] * o[0] + o[1] * o[1]) + (o[2] * o[2] + o[3] * o[3]); }
;                 if (STn) { s += __shfl_xor(s, 16); s += __shfl_xor(s, 32); q += __shfl_xor(q, 16); q += __shfl_xor(q, 32);
;                     if (fq == 0) *(GASP f32x2*)(STn + (size_t)row * 32 + (u.pn * 4 + wc) * 2) = (f32x2){s, q}; }
.LBB0_1052:
	s_or_b64 exec, exec, s[50:51]
	v_add_u32_e32 v96, s37, v191
	v_ashrrev_i32_e32 v97, 31, v96
	v_cmp_gt_i32_e32 vcc, s73, v96
	s_nop 1
	v_cndmask_b32_e32 v97, 0, v97, vcc
	s_waitcnt lgkmcnt(0)
	v_lshlrev_b64 v[98:99], 11, v[96:97]
	v_lshl_add_u64 v[98:99], s[42:43], 0, v[98:99]
	v_lshl_add_u64 v[98:99], v[174:175], 1, v[98:99]
	global_load_dwordx2 v[100:101], v[98:99], off
	global_load_dwordx2 v[102:103], v[98:99], off offset:32
	global_load_dwordx2 v[104:105], v[98:99], off offset:256
	global_load_dwordx2 v[106:107], v[98:99], off offset:288
	ds_read_b64 v[108:109], v192
	s_waitcnt vmcnt(3)
	v_lshlrev_b32_e32 v111, 16, v101
	v_and_b32_e32 v112, 0xffff0000, v101
	s_waitcnt vmcnt(2)
	v_lshlrev_b32_e32 v120, 16, v103
	v_and_b32_e32 v121, 0xffff0000, v103
	v_lshlrev_b32_e32 v110, 16, v100
	v_and_b32_e32 v100, 0xffff0000, v100
	v_lshlrev_b32_e32 v118, 16, v102
	v_and_b32_e32 v119, 0xffff0000, v102
	s_waitcnt vmcnt(1)
	v_lshlrev_b32_e32 v122, 16, v104
	v_and_b32_e32 v123, 0xffff0000, v104
	v_lshlrev_b32_e32 v124, 16, v105
	v_and_b32_e32 v125, 0xffff0000, v105
	s_waitcnt lgkmcnt(0)
	v_sub_f32_e32 v103, v112, v108
	v_sub_f32_e32 v102, v111, v108
	v_sub_f32_e32 v105, v121, v108
	v_sub_f32_e32 v104, v120, v108
	s_waitcnt vmcnt(0)
	v_lshlrev_b32_e32 v126, 16, v106
	v_and_b32_e32 v127, 0xffff0000, v106
	v_lshlrev_b32_e32 v128, 16, v107
	v_and_b32_e32 v129, 0xffff0000, v107
	v_sub_f32_e32 v101, v100, v108
	v_sub_f32_e32 v100, v110, v108
	v_sub_f32_e32 v107, v119, v108
	v_sub_f32_e32 v106, v118, v108
	v_pk_mul_f32 v[102:103], v[108:109], v[102:103] op_sel:[1,0]
	v_pk_mul_f32 v[104:105], v[108:109], v[104:105] op_sel:[1,0]
	v_sub_f32_e32 v111, v125, v108
	v_sub_f32_e32 v110, v124, v108
	v_sub_f32_e32 v113, v123, v108
	v_sub_f32_e32 v112, v122, v108
	v_sub_f32_e32 v117, v127, v108
	v_sub_f32_e32 v116, v126, v108
	v_pk_mul_f32 v[100:101], v[108:109], v[100:101] op_sel:[1,0]
	v_pk_mul_f32 v[106:107], v[108:109], v[106:107] op_sel:[1,0]
	v_pk_fma_f32 v[102:103], v[78:79], v[102:103], v[66:67]
	v_pk_fma_f32 v[104:105], v[70:71], v[104:105], v[82:83]
	v_sub_f32_e32 v115, v129, v108
	v_sub_f32_e32 v114, v128, v108
	v_pk_mul_f32 v[112:113], v[108:109], v[112:113] op_sel:[1,0]
	v_pk_mul_f32 v[110:111], v[108:109], v[110:111] op_sel:[1,0]
	v_pk_mul_f32 v[116:117], v[108:109], v[116:117] op_sel:[1,0]
	v_pk_fma_f32 v[100:101], v[76:77], v[100:101], v[64:65]
	v_pk_fma_f32 v[106:107], v[68:69], v[106:107], v[80:81]
	v_pk_fma_f32 v[62:63], v[102:103], s[34:35], v[62:63] op_sel_hi:[1,0,1]
	v_cndmask_b32_e64 v103, v105, v121, s[10:11]
	v_cndmask_b32_e64 v102, v104, v120, s[10:11]
	v_pk_mul_f32 v[108:109], v[108:109], v[114:115] op_sel:[1,0]
	v_pk_fma_f32 v[110:111], v[74:75], v[110:111], v[86:87]
	v_pk_fma_f32 v[112:113], v[72:73], v[112:113], v[84:85]
	v_pk_fma_f32 v[114:115], v[88:89], v[116:117], v[92:93]
	v_pk_fma_f32 v[60:61], v[100:101], s[34:35], v[60:61] op_sel_hi:[1,0,1]
	v_cndmask_b32_e64 v101, v107, v119, s[10:11]
	v_cndmask_b32_e64 v100, v106, v118, s[10:11]
	v_pk_fma_f32 v[58:59], v[102:103], s[34:35], v[58:59] op_sel_hi:[1,0,1]
	v_cndmask_b32_e64 v104, v112, v122, s[10:11]
	v_cndmask_b32_e64 v106, v110, v124, s[10:11]
	v_cndmask_b32_e64 v110, v114, v126, s[10:11]
	v_cvt_pk_bf16_f32 v236, v60, v61
	v_add_f32_e32 v114, v60, v61
	v_mul_f32_e32 v119, v60, v60
	v_mul_f32_e32 v61, v61, v61
	v_pk_fma_f32 v[56:57], v[100:101], s[34:35], v[56:57] op_sel_hi:[1,0,1]
	v_mul_f32_e32 v60, v58, v58
	v_cndmask_b32_e64 v105, v113, v123, s[10:11]
	v_cvt_pk_bf16_f32 v237, v62, v63
	v_add_f32_e32 v116, v62, v63
	v_mul_f32_e32 v121, v62, v62
	v_mul_f32_e32 v63, v63, v63
	v_pk_fma_f32 v[122:123], v[58:59], v[58:59], v[60:61] op_sel_hi:[1,1,0]
	v_mov_b32_e32 v118, v56
	v_mov_b32_e32 v60, v57
	v_mov_b32_e32 v120, v58
	v_mov_b32_e32 v62, v59
	v_pk_fma_f32 v[108:109], v[90:91], v[108:109], v[94:95]
	v_cndmask_b32_e64 v107, v111, v125, s[10:11]
	v_cndmask_b32_e64 v111, v115, v127, s[10:11]
	v_cvt_pk_bf16_f32 v238, v56, v57
	v_mul_f32_e32 v115, v56, v56
	v_mul_f32_e32 v117, v57, v57
	v_pk_add_f32 v[56:57], v[118:119], v[60:61]
	v_pk_add_f32 v[60:61], v[120:121], v[62:63]
	v_pk_fma_f32 v[54:55], v[106:107], s[34:35], v[54:55] op_sel_hi:[1,0,1]
	v_pk_fma_f32 v[52:53], v[104:105], s[34:35], v[52:53] op_sel_hi:[1,0,1]
	v_cndmask_b32_e64 v109, v109, v129, s[10:11]
	v_cndmask_b32_e64 v108, v108, v128, s[10:11]
	v_pk_add_f32 v[56:57], v[56:57], v[60:61]
	v_pk_add_f32 v[60:61], v[114:115], v[116:117]
	v_mov_b32_e32 v165, v123
	v_mul_f32_e32 v103, v52, v52
	v_mul_f32_e32 v105, v53, v53
	v_mul_f32_e32 v107, v54, v54
	v_mul_f32_e32 v113, v55, v55
	v_pk_fma_f32 v[108:109], v[108:109], s[34:35], v[50:51] op_sel_hi:[1,0,1]
	v_pk_fma_f32 v[110:111], v[110:111], s[34:35], v[48:49] op_sel_hi:[1,0,1]
	v_pk_add_f32 v[60:61], v[60:61], v[164:165]
	v_mov_b32_e32 v102, v52
	v_mov_b32_e32 v104, v53
	v_mov_b32_e32 v106, v54
	v_mov_b32_e32 v112, v55
	v_mul_f32_e32 v49, v110, v110
	v_mul_f32_e32 v51, v111, v111
	v_mul_f32_e32 v125, v108, v108
	v_mul_f32_e32 v127, v109, v109
	v_pk_add_f32 v[56:57], v[56:57], v[60:61]
	v_pk_add_f32 v[60:61], v[102:103], v[104:105]
	v_pk_add_f32 v[62:63], v[106:107], v[112:113]
	v_mov_b32_e32 v48, v110
	v_mov_b32_e32 v50, v111
	v_mov_b32_e32 v124, v108
	v_mov_b32_e32 v126, v109
	v_pk_add_f32 v[60:61], v[60:61], v[62:63]
	v_pk_add_f32 v[48:49], v[48:49], v[50:51]
	v_pk_add_f32 v[50:51], v[124:125], v[126:127]
	v_pk_add_f32 v[56:57], v[56:57], v[60:61]
	v_pk_add_f32 v[48:49], v[48:49], v[50:51]
	v_cvt_pk_bf16_f32 v240, v52, v53
	v_pk_add_f32 v[48:49], v[56:57], v[48:49]
	ds_bpermute_b32 v50, v148, v48
	ds_bpermute_b32 v51, v148, v49
	v_cvt_pk_bf16_f32 v241, v54, v55
	v_cvt_pk_bf16_f32 v239, v58, v59
	v_cvt_pk_bf16_f32 v242, v110, v111
	s_waitcnt lgkmcnt(0)
	v_pk_add_f32 v[48:49], v[48:49], v[50:51]
	ds_bpermute_b32 v50, v149, v48
	ds_bpermute_b32 v51, v149, v49
	v_cvt_pk_bf16_f32 v243, v108, v109
	s_nop 1
	v_permlane16_swap_b32_e32 v236, v238
	v_permlane16_swap_b32_e32 v237, v239
	v_lshl_add_u64 v[244:245], v[98:99], 0, v[246:247]
	global_store_dwordx4 v[244:245], v[236:239], off
	s_nop 1
	v_permlane16_swap_b32_e32 v240, v242
	v_permlane16_swap_b32_e32 v241, v243
	global_store_dwordx4 v[244:245], v[240:243], off offset:256
	s_and_saveexec_b64 s[50:51], s[8:9]
	s_cbranch_execz .LBB0_1054
	s_waitcnt lgkmcnt(0)
	v_pk_add_f32 v[48:49], v[48:49], v[50:51]
	v_lshlrev_b64 v[50:51], 7, v[96:97]
	v_lshl_add_u64 v[50:51], s[24:25], 0, v[50:51]
	v_lshl_add_u64 v[50:51], s[14:15], 2, v[50:51]
	global_store_dwordx2 v[50:51], v[48:49], off
; #define GASP __attribute__((address_space(1)))
;     __device__ __forceinline__ void operator()(Acc& acc, const Unit& u, int wr, int wc, int fr, int fq, LAS unsigned char* lds) const {
;     ...
;                 const int rl = ai * HALF + wr * 64 + m * 16 + fr, row = u.pm * BM + rl;
;                 const float* rp = (row < split) ? res0 + (size_t)row * D : res1 + (size_t)(row - split) * D;
;                 float* op = out + (size_t)row * D;
;                 f32x2 st = (f32x2){0.f, 1.f}; if (STp) st = SL[rl];
;                 float s = 0.f, q = 0.f;
; #pragma unroll
;                 for (int bj = 0; bj < 2; ++bj)
; #pragma unroll
;                     for (int n = 0; n < 2; ++n) { const int c = col0 + bj * HALF + n * 16; f32x4 r;
;                         if (resb) { const u32x2 w = *(const GASP u32x2*)(resb + (size_t)row * D + c);
;                             r = (f32x4){__uint_as_float(w.x << 16), __uint_as_float(w.x & 0xffff0000u), __uint_as_float(w.y << 16), __uint_as_float(w.y & 0xffff0000u)}; }
;                         else r = *(const GASP f32x4*)(rp + c);
;                         if (STp) r = (r - st[0]) * st[1] * gg[bj][n] + bb[bj][n];
;                         const f32x4 o = r * ALPHA + acc[ai][bj][m][n] * scale;
;                         if (out) *(GASP f32x4*)(op + c) = o;
;                         if (ob) { u32x2 w; w.x = pk2(o[0], o[1]); w.y = pk2(o[2], o[3]); *(GASP u32x2*)(ob + (size_t)row * D + c) = w; }
;                         s += (o[0] + o[1]) + (o[2] + o[3]); q += (o[0] * o[0] + o[1] * o[1]) + (o[2] * o[2] + o[3] * o[3]); }
;                 if (STn) { s += __shfl_xor(s, 16); s += __shfl_xor(s, 32); q += __shfl_xor(q, 16); q += __shfl_xor(q, 32);
;                     if (fq == 0) *(GASP f32x2*)(STn + (size_t)row * 32 + (u.pn * 4 + wc) * 2) = (f32x2){s, q}; }
.LBB0_1054:
	s_or_b64 exec, exec, s[50:51]
	v_add_u32_e32 v48, s37, v193
	v_ashrrev_i32_e32 v49, 31, v48
	v_cmp_gt_i32_e32 vcc, s73, v48
	s_nop 1
	v_cndmask_b32_e32 v49, 0, v49, vcc
	s_waitcnt lgkmcnt(0)
	v_lshlrev_b64 v[50:51], 11, v[48:49]
	v_lshl_add_u64 v[50:51], s[42:43], 0, v[50:51]
	v_lshl_add_u64 v[50:51], v[174:175], 1, v[50:51]
	global_load_dwordx2 v[52:53], v[50:51], off
	global_load_dwordx2 v[54:55], v[50:51], off offset:32
	global_load_dwordx2 v[56:57], v[50:51], off offset:256
	global_load_dwordx2 v[58:59], v[50:51], off offset:288
	ds_read_b64 v[60:61], v194
	s_waitcnt vmcnt(3)
	v_lshlrev_b32_e32 v63, 16, v53
	v_and_b32_e32 v96, 0xffff0000, v53
	s_waitcnt vmcnt(2)
	v_lshlrev_b32_e32 v104, 16, v55
	v_and_b32_e32 v105, 0xffff0000, v55
	v_lshlrev_b32_e32 v62, 16, v52
	v_and_b32_e32 v52, 0xffff0000, v52
	v_lshlrev_b32_e32 v102, 16, v54
	v_and_b32_e32 v103, 0xffff0000, v54
	s_waitcnt vmcnt(1)
	v_lshlrev_b32_e32 v106, 16, v56
	v_and_b32_e32 v107, 0xffff0000, v56
	v_lshlrev_b32_e32 v108, 16, v57
	v_and_b32_e32 v109, 0xffff0000, v57
	s_waitcnt lgkmcnt(0)
	v_sub_f32_e32 v55, v96, v60
	v_sub_f32_e32 v54, v63, v60
	v_sub_f32_e32 v57, v105, v60
	v_sub_f32_e32 v56, v104, v60
	s_waitcnt vmcnt(0)
	v_lshlrev_b32_e32 v110, 16, v58
	v_and_b32_e32 v111, 0xffff0000, v58
	v_lshlrev_b32_e32 v112, 16, v59
	v_and_b32_e32 v113, 0xffff0000, v59
	v_sub_f32_e32 v53, v52, v60
	v_sub_f32_e32 v52, v62, v60
	v_sub_f32_e32 v59, v103, v60
	v_sub_f32_e32 v58, v102, v60
	v_pk_mul_f32 v[54:55], v[60:61], v[54:55] op_sel:[1,0]
	v_pk_mul_f32 v[56:57], v[60:61], v[56:57] op_sel:[1,0]
	v_sub_f32_e32 v63, v109, v60
	v_sub_f32_e32 v62, v108, v60
	v_sub_f32_e32 v97, v107, v60
	v_sub_f32_e32 v96, v106, v60
	v_sub_f32_e32 v101, v111, v60
	v_sub_f32_e32 v100, v110, v60
	v_pk_mul_f32 v[52:53], v[60:61], v[52:53] op_sel:[1,0]
	v_pk_mul_f32 v[58:59], v[60:61], v[58:59] op_sel:[1,0]
	v_pk_fma_f32 v[54:55], v[78:79], v[54:55], v[66:67]
	v_pk_fma_f32 v[56:57], v[70:71], v[56:57], v[82:83]
	v_sub_f32_e32 v99, v113, v60
	v_sub_f32_e32 v98, v112, v60
	v_pk_mul_f32 v[96:97], v[60:61], v[96:97] op_sel:[1,0]
	v_pk_mul_f32 v[62:63], v[60:61], v[62:63] op_sel:[1,0]
	v_pk_mul_f32 v[100:101], v[60:61], v[100:101] op_sel:[1,0]
	v_pk_fma_f32 v[52:53], v[76:77], v[52:53], v[64:65]
	v_pk_fma_f32 v[58:59], v[68:69], v[58:59], v[80:81]
	v_pk_fma_f32 v[46:47], v[54:55], s[34:35], v[46:47] op_sel_hi:[1,0,1]
	v_cndmask_b32_e64 v55, v57, v105, s[10:11]
	v_cndmask_b32_e64 v54, v56, v104, s[10:11]
	v_pk_mul_f32 v[60:61], v[60:61], v[98:99] op_sel:[1,0]
	v_pk_fma_f32 v[62:63], v[74:75], v[62:63], v[86:87]
	v_pk_fma_f32 v[96:97], v[72:73], v[96:97], v[84:85]
	v_pk_fma_f32 v[98:99], v[88:89], v[100:101], v[92:93]
	v_pk_fma_f32 v[44:45], v[52:53], s[34:35], v[44:45] op_sel_hi:[1,0,1]
	v_cndmask_b32_e64 v53, v59, v103, s[10:11]
	v_cndmask_b32_e64 v52, v58, v102, s[10:11]
	v_pk_fma_f32 v[42:43], v[54:55], s[34:35], v[42:43] op_sel_hi:[1,0,1]
	v_cndmask_b32_e64 v56, v96, v106, s[10:11]
	v_cndmask_b32_e64 v58, v62, v108, s[10:11]
	v_cndmask_b32_e64 v62, v98, v110, s[10:11]
	v_cvt_pk_bf16_f32 v236, v44, v45
	v_add_f32_e32 v98, v44, v45
	v_mul_f32_e32 v103, v44, v44
	v_mul_f32_e32 v45, v45, v45
	v_pk_fma_f32 v[40:41], v[52:53], s[34:35], v[40:41] op_sel_hi:[1,0,1]
	v_mul_f32_e32 v44, v42, v42
	v_cndmask_b32_e64 v57, v97, v107, s[10:11]
	v_cvt_pk_bf16_f32 v237, v46, v47
	v_add_f32_e32 v100, v46, v47
	v_mul_f32_e32 v105, v46, v46
	v_mul_f32_e32 v47, v47, v47
	v_pk_fma_f32 v[106:107], v[42:43], v[42:43], v[44:45] op_sel_hi:[1,1,0]
	v_mov_b32_e32 v102, v40
	v_mov_b32_e32 v44, v41
	v_mov_b32_e32 v104, v42
	v_mov_b32_e32 v46, v43
	v_pk_fma_f32 v[60:61], v[90:91], v[60:61], v[94:95]
	v_cndmask_b32_e64 v59, v63, v109, s[10:11]
	v_cndmask_b32_e64 v63, v99, v111, s[10:11]
	v_cvt_pk_bf16_f32 v238, v40, v41
	v_mul_f32_e32 v99, v40, v40
	v_mul_f32_e32 v101, v41, v41
	v_pk_add_f32 v[40:41], v[102:103], v[44:45]
	v_pk_add_f32 v[44:45], v[104:105], v[46:47]
	v_pk_fma_f32 v[38:39], v[58:59], s[34:35], v[38:39] op_sel_hi:[1,0,1]
	v_pk_fma_f32 v[36:37], v[56:57], s[34:35], v[36:37] op_sel_hi:[1,0,1]
	v_cndmask_b32_e64 v61, v61, v113, s[10:11]
	v_cndmask_b32_e64 v60, v60, v112, s[10:11]
	v_pk_add_f32 v[40:41], v[40:41], v[44:45]
	v_pk_add_f32 v[44:45], v[98:99], v[100:101]
	v_mov_b32_e32 v165, v107
	v_mul_f32_e32 v55, v36, v36
	v_mul_f32_e32 v57, v37, v37
	v_mul_f32_e32 v59, v38, v38
	v_mul_f32_e32 v97, v39, v39
	v_pk_fma_f32 v[60:61], v[60:61], s[34:35], v[34:35] op_sel_hi:[1,0,1]
	v_pk_fma_f32 v[62:63], v[62:63], s[34:35], v[32:33] op_sel_hi:[1,0,1]
	v_pk_add_f32 v[44:45], v[44:45], v[164:165]
	v_mov_b32_e32 v54, v36
	v_mov_b32_e32 v56, v37
	v_mov_b32_e32 v58, v38
	v_mov_b32_e32 v96, v39
	v_mul_f32_e32 v33, v62, v62
	v_mul_f32_e32 v35, v63, v63
	v_mul_f32_e32 v109, v60, v60
	v_mul_f32_e32 v111, v61, v61
	v_pk_add_f32 v[40:41], v[40:41], v[44:45]
	v_pk_add_f32 v[44:45], v[54:55], v[56:57]
	v_pk_add_f32 v[46:47], v[58:59], v[96:97]
	v_mov_b32_e32 v32, v62
	v_mov_b32_e32 v34, v63
	v_mov_b32_e32 v108, v60
	v_mov_b32_e32 v110, v61
	v_pk_add_f32 v[44:45], v[44:45], v[46:47]
	v_pk_add_f32 v[32:33], v[32:33], v[34:35]
	v_pk_add_f32 v[34:35], v[108:109], v[110:111]
	v_pk_add_f32 v[40:41], v[40:41], v[44:45]
	v_pk_add_f32 v[32:33], v[32:33], v[34:35]
	v_cvt_pk_bf16_f32 v240, v36, v37
	v_pk_add_f32 v[32:33], v[40:41], v[32:33]
	ds_bpermute_b32 v34, v148, v32
	ds_bpermute_b32 v35, v148, v33
	v_cvt_pk_bf16_f32 v241, v38, v39
	v_cvt_pk_bf16_f32 v239, v42, v43
	v_cvt_pk_bf16_f32 v242, v62, v63
	s_waitcnt lgkmcnt(0)
	v_pk_add_f32 v[32:33], v[32:33], v[34:35]
	ds_bpermute_b32 v34, v149, v32
	ds_bpermute_b32 v35, v149, v33
	v_cvt_pk_bf16_f32 v243, v60, v61
	s_nop 1
	v_permlane16_swap_b32_e32 v236, v238
	v_permlane16_swap_b32_e32 v237, v239
	v_lshl_add_u64 v[244:245], v[50:51], 0, v[246:247]
	global_store_dwordx4 v[244:245], v[236:239], off
	s_nop 1
	v_permlane16_swap_b32_e32 v240, v242
	v_permlane16_swap_b32_e32 v241, v243
	global_store_dwordx4 v[244:245], v[240:243], off offset:256
	s_and_saveexec_b64 s[50:51], s[8:9]
	s_cbranch_execz .LBB0_1056
	s_waitcnt lgkmcnt(0)
	v_pk_add_f32 v[32:33], v[32:33], v[34:35]
	v_lshlrev_b64 v[34:35], 7, v[48:49]
	v_lshl_add_u64 v[34:35], s[24:25], 0, v[34:35]
	v_lshl_add_u64 v[34:35], s[14:15], 2, v[34:35]
	global_store_dwordx2 v[34:35], v[32:33], off
; #define GASP __attribute__((address_space(1)))
;     __device__ __forceinline__ void operator()(Acc& acc, const Unit& u, int wr, int wc, int fr, int fq, LAS unsigned char* lds) const {
;     ...
;                 const int rl = ai * HALF + wr * 64 + m * 16 + fr, row = u.pm * BM + rl;
;                 const float* rp = (row < split) ? res0 + (size_t)row * D : res1 + (size_t)(row - split) * D;
;                 float* op = out + (size_t)row * D;
;                 f32x2 st = (f32x2){0.f, 1.f}; if (STp) st = SL[rl];
;                 float s = 0.f, q = 0.f;
; #pragma unroll
;                 for (int bj = 0; bj < 2; ++bj)
; #pragma unroll
;                     for (int n = 0; n < 2; ++n) { const int c = col0 + bj * HALF + n * 16; f32x4 r;
;                         if (resb) { const u32x2 w = *(const GASP u32x2*)(resb + (size_t)row * D + c);
;                             r = (f32x4){__uint_as_float(w.x << 16), __uint_as_float(w.x & 0xffff0000u), __uint_as_float(w.y << 16), __uint_as_float(w.y & 0xffff0000u)}; }
;                         else r = *(const GASP f32x4*)(rp + c);
;                         if (STp) r = (r - st[0]) * st[1] * gg[bj][n] + bb[bj][n];
;                         const f32x4 o = r * ALPHA + acc[ai][bj][m][n] * scale;
;                         if (out) *(GASP f32x4*)(op + c) = o;
;                         if (ob) { u32x2 w; w.x = pk2(o[0], o[1]); w.y = pk2(o[2], o[3]); *(GASP u32x2*)(ob + (size_t)row * D + c) = w; }
;                         s += (o[0] + o[1]) + (o[2] + o[3]); q += (o[0] * o[0] + o[1] * o[1]) + (o[2] * o[2] + o[3] * o[3]); }
;                 if (STn) { s += __shfl_xor(s, 16); s += __shfl_xor(s, 32); q += __shfl_xor(q, 16); q += __shfl_xor(q, 32);
;                     if (fq == 0) *(GASP f32x2*)(STn + (size_t)row * 32 + (u.pn * 4 + wc) * 2) = (f32x2){s, q}; }
.LBB0_1056:
	s_or_b64 exec, exec, s[50:51]
	v_add_u32_e32 v32, s37, v195
	v_ashrrev_i32_e32 v33, 31, v32
	v_cmp_gt_i32_e32 vcc, s73, v32
	s_nop 1
	v_cndmask_b32_e32 v33, 0, v33, vcc
	s_waitcnt lgkmcnt(0)
	v_lshlrev_b64 v[34:35], 11, v[32:33]
	v_lshl_add_u64 v[34:35], s[42:43], 0, v[34:35]
	v_lshl_add_u64 v[34:35], v[174:175], 1, v[34:35]
	global_load_dwordx2 v[36:37], v[34:35], off
	global_load_dwordx2 v[38:39], v[34:35], off offset:32
	global_load_dwordx2 v[40:41], v[34:35], off offset:256
	global_load_dwordx2 v[42:43], v[34:35], off offset:288
	ds_read_b64 v[44:45], v196
	s_waitcnt vmcnt(3)
	v_lshlrev_b32_e32 v47, 16, v37
	v_and_b32_e32 v48, 0xffff0000, v37
	s_waitcnt vmcnt(2)
	v_lshlrev_b32_e32 v56, 16, v39
	v_and_b32_e32 v57, 0xffff0000, v39
	v_lshlrev_b32_e32 v46, 16, v36
	v_and_b32_e32 v36, 0xffff0000, v36
	v_lshlrev_b32_e32 v54, 16, v38
	v_and_b32_e32 v55, 0xffff0000, v38
	s_waitcnt vmcnt(1)
	v_lshlrev_b32_e32 v58, 16, v40
	v_and_b32_e32 v59, 0xffff0000, v40
	v_lshlrev_b32_e32 v60, 16, v41
	v_and_b32_e32 v61, 0xffff0000, v41
	s_waitcnt lgkmcnt(0)
	v_sub_f32_e32 v39, v48, v44
	v_sub_f32_e32 v38, v47, v44
	v_sub_f32_e32 v41, v57, v44
	v_sub_f32_e32 v40, v56, v44
	s_waitcnt vmcnt(0)
	v_lshlrev_b32_e32 v62, 16, v42
	v_and_b32_e32 v63, 0xffff0000, v42
	v_lshlrev_b32_e32 v96, 16, v43
	v_and_b32_e32 v97, 0xffff0000, v43
	v_sub_f32_e32 v37, v36, v44
	v_sub_f32_e32 v36, v46, v44
	v_sub_f32_e32 v43, v55, v44
	v_sub_f32_e32 v42, v54, v44
	v_pk_mul_f32 v[38:39], v[44:45], v[38:39] op_sel:[1,0]
	v_pk_mul_f32 v[40:41], v[44:45], v[40:41] op_sel:[1,0]
	v_sub_f32_e32 v47, v61, v44
	v_sub_f32_e32 v46, v60, v44
	v_sub_f32_e32 v49, v59, v44
	v_sub_f32_e32 v48, v58, v44
	v_sub_f32_e32 v53, v63, v44
	v_sub_f32_e32 v52, v62, v44
	v_pk_mul_f32 v[36:37], v[44:45], v[36:37] op_sel:[1,0]
	v_pk_mul_f32 v[42:43], v[44:45], v[42:43] op_sel:[1,0]
	v_pk_fma_f32 v[38:39], v[78:79], v[38:39], v[66:67]
	v_pk_fma_f32 v[40:41], v[70:71], v[40:41], v[82:83]
	v_sub_f32_e32 v51, v97, v44
	v_sub_f32_e32 v50, v96, v44
	v_pk_mul_f32 v[48:49], v[44:45], v[48:49] op_sel:[1,0]
	v_pk_mul_f32 v[46:47], v[44:45], v[46:47] op_sel:[1,0]
	v_pk_mul_f32 v[52:53], v[44:45], v[52:53] op_sel:[1,0]
	v_pk_fma_f32 v[36:37], v[76:77], v[36:37], v[64:65]
	v_pk_fma_f32 v[42:43], v[68:69], v[42:43], v[80:81]
	v_pk_fma_f32 v[30:31], v[38:39], s[34:35], v[30:31] op_sel_hi:[1,0,1]
	v_cndmask_b32_e64 v39, v41, v57, s[10:11]
	v_cndmask_b32_e64 v38, v40, v56, s[10:11]
	v_pk_mul_f32 v[44:45], v[44:45], v[50:51] op_sel:[1,0]
	v_pk_fma_f32 v[46:47], v[74:75], v[46:47], v[86:87]
	v_pk_fma_f32 v[48:49], v[72:73], v[48:49], v[84:85]
	v_pk_fma_f32 v[50:51], v[88:89], v[52:53], v[92:93]
	v_pk_fma_f32 v[28:29], v[36:37], s[34:35], v[28:29] op_sel_hi:[1,0,1]
	v_cndmask_b32_e64 v37, v43, v55, s[10:11]
	v_cndmask_b32_e64 v36, v42, v54, s[10:11]
	v_pk_fma_f32 v[26:27], v[38:39], s[34:35], v[26:27] op_sel_hi:[1,0,1]
	v_cndmask_b32_e64 v40, v48, v58, s[10:11]
	v_cndmask_b32_e64 v42, v46, v60, s[10:11]
	v_cndmask_b32_e64 v46, v50, v62, s[10:11]
	v_cvt_pk_bf16_f32 v236, v28, v29
	v_add_f32_e32 v50, v28, v29
	v_mul_f32_e32 v55, v28, v28
	v_mul_f32_e32 v29, v29, v29
	v_pk_fma_f32 v[24:25], v[36:37], s[34:35], v[24:25] op_sel_hi:[1,0,1]
	v_mul_f32_e32 v28, v26, v26
	v_cndmask_b32_e64 v41, v49, v59, s[10:11]
	v_cvt_pk_bf16_f32 v237, v30, v31
	v_add_f32_e32 v52, v30, v31
	v_mul_f32_e32 v57, v30, v30
	v_mul_f32_e32 v31, v31, v31
	v_pk_fma_f32 v[58:59], v[26:27], v[26:27], v[28:29] op_sel_hi:[1,1,0]
	v_mov_b32_e32 v54, v24
	v_mov_b32_e32 v28, v25
	v_mov_b32_e32 v56, v26
	v_mov_b32_e32 v30, v27
	v_pk_fma_f32 v[44:45], v[90:91], v[44:45], v[94:95]
	v_cndmask_b32_e64 v43, v47, v61, s[10:11]
	v_cndmask_b32_e64 v47, v51, v63, s[10:11]
	v_cvt_pk_bf16_f32 v238, v24, v25
	v_mul_f32_e32 v51, v24, v24
	v_mul_f32_e32 v53, v25, v25
	v_pk_add_f32 v[24:25], v[54:55], v[28:29]
	v_pk_add_f32 v[28:29], v[56:57], v[30:31]
	v_pk_fma_f32 v[22:23], v[42:43], s[34:35], v[22:23] op_sel_hi:[1,0,1]
	v_pk_fma_f32 v[20:21], v[40:41], s[34:35], v[20:21] op_sel_hi:[1,0,1]
	v_cndmask_b32_e64 v45, v45, v97, s[10:11]
	v_cndmask_b32_e64 v44, v44, v96, s[10:11]
	v_pk_add_f32 v[24:25], v[24:25], v[28:29]
	v_pk_add_f32 v[28:29], v[50:51], v[52:53]
	v_mov_b32_e32 v165, v59
	v_mul_f32_e32 v39, v20, v20
	v_mul_f32_e32 v41, v21, v21
	v_mul_f32_e32 v43, v22, v22
	v_mul_f32_e32 v49, v23, v23
	v_pk_fma_f32 v[44:45], v[44:45], s[34:35], v[18:19] op_sel_hi:[1,0,1]
	v_pk_fma_f32 v[46:47], v[46:47], s[34:35], v[16:17] op_sel_hi:[1,0,1]
	v_pk_add_f32 v[28:29], v[28:29], v[164:165]
	v_mov_b32_e32 v38, v20
	v_mov_b32_e32 v40, v21
	v_mov_b32_e32 v42, v22
	v_mov_b32_e32 v48, v23
	v_mul_f32_e32 v17, v46, v46
	v_mul_f32_e32 v19, v47, v47
	v_mul_f32_e32 v61, v44, v44
	v_mul_f32_e32 v63, v45, v45
	v_pk_add_f32 v[24:25], v[24:25], v[28:29]
	v_pk_add_f32 v[28:29], v[38:39], v[40:41]
	v_pk_add_f32 v[30:31], v[42:43], v[48:49]
	v_mov_b32_e32 v16, v46
	v_mov_b32_e32 v18, v47
	v_mov_b32_e32 v60, v44
	v_mov_b32_e32 v62, v45
	v_pk_add_f32 v[28:29], v[28:29], v[30:31]
	v_pk_add_f32 v[16:17], v[16:17], v[18:19]
	v_pk_add_f32 v[18:19], v[60:61], v[62:63]
	v_pk_add_f32 v[24:25], v[24:25], v[28:29]
	v_pk_add_f32 v[16:17], v[16:17], v[18:19]
	v_cvt_pk_bf16_f32 v240, v20, v21
	v_pk_add_f32 v[16:17], v[24:25], v[16:17]
	ds_bpermute_b32 v18, v148, v16
	ds_bpermute_b32 v19, v148, v17
	v_cvt_pk_bf16_f32 v241, v22, v23
	v_cvt_pk_bf16_f32 v239, v26, v27
	v_cvt_pk_bf16_f32 v242, v46, v47
	s_waitcnt lgkmcnt(0)
	v_pk_add_f32 v[16:17], v[16:17], v[18:19]
	ds_bpermute_b32 v18, v149, v16
	ds_bpermute_b32 v19, v149, v17
	v_cvt_pk_bf16_f32 v243, v44, v45
	s_nop 1
	v_permlane16_swap_b32_e32 v236, v238
	v_permlane16_swap_b32_e32 v237, v239
	v_lshl_add_u64 v[244:245], v[34:35], 0, v[246:247]
	global_store_dwordx4 v[244:245], v[236:239], off
	s_nop 1
	v_permlane16_swap_b32_e32 v240, v242
	v_permlane16_swap_b32_e32 v241, v243
	global_store_dwordx4 v[244:245], v[240:243], off offset:256
	s_and_saveexec_b64 s[50:51], s[8:9]
	s_cbranch_execz .LBB0_1058
	s_waitcnt lgkmcnt(0)
	v_pk_add_f32 v[16:17], v[16:17], v[18:19]
	v_lshlrev_b64 v[18:19], 7, v[32:33]
	v_lshl_add_u64 v[18:19], s[24:25], 0, v[18:19]
	v_lshl_add_u64 v[18:19], s[14:15], 2, v[18:19]
	global_store_dwordx2 v[18:19], v[16:17], off
; #define GASP __attribute__((address_space(1)))
;     __device__ __forceinline__ void operator()(Acc& acc, const Unit& u, int wr, int wc, int fr, int fq, LAS unsigned char* lds) const {
;     ...
;                 const int rl = ai * HALF + wr * 64 + m * 16 + fr, row = u.pm * BM + rl;
;                 const float* rp = (row < split) ? res0 + (size_t)row * D : res1 + (size_t)(row - split) * D;
;                 float* op = out + (size_t)row * D;
;                 f32x2 st = (f32x2){0.f, 1.f}; if (STp) st = SL[rl];
;                 float s = 0.f, q = 0.f;
; #pragma unroll
;                 for (int bj = 0; bj < 2; ++bj)
; #pragma unroll
;                     for (int n = 0; n < 2; ++n) { const int c = col0 + bj * HALF + n * 16; f32x4 r;
;                         if (resb) { const u32x2 w = *(const GASP u32x2*)(resb + (size_t)row * D + c);
;                             r = (f32x4){__uint_as_float(w.x << 16), __uint_as_float(w.x & 0xffff0000u), __uint_as_float(w.y << 16), __uint_as_float(w.y & 0xffff0000u)}; }
;                         else r = *(const GASP f32x4*)(rp + c);
;                         if (STp) r = (r - st[0]) * st[1] * gg[bj][n] + bb[bj][n];
;                         const f32x4 o = r * ALPHA + acc[ai][bj][m][n] * scale;
;                         if (out) *(GASP f32x4*)(op + c) = o;
;                         if (ob) { u32x2 w; w.x = pk2(o[0], o[1]); w.y = pk2(o[2], o[3]); *(GASP u32x2*)(ob + (size_t)row * D + c) = w; }
;                         s += (o[0] + o[1]) + (o[2] + o[3]); q += (o[0] * o[0] + o[1] * o[1]) + (o[2] * o[2] + o[3] * o[3]); }
;                 if (STn) { s += __shfl_xor(s, 16); s += __shfl_xor(s, 32); q += __shfl_xor(q, 16); q += __shfl_xor(q, 32);
;                     if (fq == 0) *(GASP f32x2*)(STn + (size_t)row * 32 + (u.pn * 4 + wc) * 2) = (f32x2){s, q}; }
.LBB0_1058:
	s_or_b64 exec, exec, s[50:51]
	v_add_u32_e32 v16, s37, v197
	v_ashrrev_i32_e32 v17, 31, v16
	v_cmp_gt_i32_e32 vcc, s73, v16
	s_nop 1
	v_cndmask_b32_e32 v17, 0, v17, vcc
	s_waitcnt lgkmcnt(0)
	v_lshlrev_b64 v[18:19], 11, v[16:17]
	v_lshl_add_u64 v[18:19], s[42:43], 0, v[18:19]
	v_lshl_add_u64 v[18:19], v[174:175], 1, v[18:19]
	global_load_dwordx2 v[20:21], v[18:19], off
	global_load_dwordx2 v[22:23], v[18:19], off offset:32
	global_load_dwordx2 v[24:25], v[18:19], off offset:256
	global_load_dwordx2 v[26:27], v[18:19], off offset:288
	ds_read_b64 v[28:29], v198
	s_waitcnt vmcnt(3)
	v_lshlrev_b32_e32 v31, 16, v21
	v_and_b32_e32 v32, 0xffff0000, v21
	s_waitcnt vmcnt(2)
	v_lshlrev_b32_e32 v40, 16, v23
	v_and_b32_e32 v41, 0xffff0000, v23
	v_lshlrev_b32_e32 v30, 16, v20
	v_and_b32_e32 v20, 0xffff0000, v20
	v_lshlrev_b32_e32 v38, 16, v22
	v_and_b32_e32 v39, 0xffff0000, v22
	s_waitcnt vmcnt(1)
	v_lshlrev_b32_e32 v42, 16, v24
	v_and_b32_e32 v43, 0xffff0000, v24
	v_lshlrev_b32_e32 v44, 16, v25
	v_and_b32_e32 v45, 0xffff0000, v25
	s_waitcnt lgkmcnt(0)
	v_sub_f32_e32 v23, v32, v28
	v_sub_f32_e32 v22, v31, v28
	v_sub_f32_e32 v25, v41, v28
	v_sub_f32_e32 v24, v40, v28
	s_waitcnt vmcnt(0)
	v_lshlrev_b32_e32 v46, 16, v26
	v_and_b32_e32 v47, 0xffff0000, v26
	v_lshlrev_b32_e32 v48, 16, v27
	v_and_b32_e32 v49, 0xffff0000, v27
	v_sub_f32_e32 v21, v20, v28
	v_sub_f32_e32 v20, v30, v28
	v_sub_f32_e32 v27, v39, v28
	v_sub_f32_e32 v26, v38, v28
	v_pk_mul_f32 v[22:23], v[28:29], v[22:23] op_sel:[1,0]
	v_pk_mul_f32 v[24:25], v[28:29], v[24:25] op_sel:[1,0]
	v_sub_f32_e32 v31, v45, v28
	v_sub_f32_e32 v30, v44, v28
	v_sub_f32_e32 v33, v43, v28
	v_sub_f32_e32 v32, v42, v28
	v_sub_f32_e32 v37, v47, v28
	v_sub_f32_e32 v36, v46, v28
	v_pk_mul_f32 v[20:21], v[28:29], v[20:21] op_sel:[1,0]
	v_pk_mul_f32 v[26:27], v[28:29], v[26:27] op_sel:[1,0]
	v_pk_fma_f32 v[22:23], v[78:79], v[22:23], v[66:67]
	v_pk_fma_f32 v[24:25], v[70:71], v[24:25], v[82:83]
	v_sub_f32_e32 v35, v49, v28
	v_sub_f32_e32 v34, v48, v28
	v_pk_mul_f32 v[32:33], v[28:29], v[32:33] op_sel:[1,0]
	v_pk_mul_f32 v[30:31], v[28:29], v[30:31] op_sel:[1,0]
	v_pk_mul_f32 v[36:37], v[28:29], v[36:37] op_sel:[1,0]
	v_pk_fma_f32 v[20:21], v[76:77], v[20:21], v[64:65]
	v_pk_fma_f32 v[26:27], v[68:69], v[26:27], v[80:81]
	v_pk_fma_f32 v[14:15], v[22:23], s[34:35], v[14:15] op_sel_hi:[1,0,1]
	v_cndmask_b32_e64 v23, v25, v41, s[10:11]
	v_cndmask_b32_e64 v22, v24, v40, s[10:11]
	v_pk_mul_f32 v[28:29], v[28:29], v[34:35] op_sel:[1,0]
	v_pk_fma_f32 v[30:31], v[74:75], v[30:31], v[86:87]
	v_pk_fma_f32 v[32:33], v[72:73], v[32:33], v[84:85]
	v_pk_fma_f32 v[34:35], v[88:89], v[36:37], v[92:93]
	v_pk_fma_f32 v[12:13], v[20:21], s[34:35], v[12:13] op_sel_hi:[1,0,1]
	v_cndmask_b32_e64 v21, v27, v39, s[10:11]
	v_cndmask_b32_e64 v20, v26, v38, s[10:11]
	v_pk_fma_f32 v[10:11], v[22:23], s[34:35], v[10:11] op_sel_hi:[1,0,1]
	v_cndmask_b32_e64 v24, v32, v42, s[10:11]
	v_cndmask_b32_e64 v26, v30, v44, s[10:11]
	v_cndmask_b32_e64 v30, v34, v46, s[10:11]
	v_cvt_pk_bf16_f32 v236, v12, v13
	v_add_f32_e32 v34, v12, v13
	v_mul_f32_e32 v39, v12, v12
	v_mul_f32_e32 v13, v13, v13
	v_pk_fma_f32 v[8:9], v[20:21], s[34:35], v[8:9] op_sel_hi:[1,0,1]
	v_mul_f32_e32 v12, v10, v10
	v_cndmask_b32_e64 v25, v33, v43, s[10:11]
	v_cvt_pk_bf16_f32 v237, v14, v15
	v_add_f32_e32 v36, v14, v15
	v_mul_f32_e32 v41, v14, v14
	v_mul_f32_e32 v15, v15, v15
	v_pk_fma_f32 v[42:43], v[10:11], v[10:11], v[12:13] op_sel_hi:[1,1,0]
	v_mov_b32_e32 v38, v8
	v_mov_b32_e32 v12, v9
	v_mov_b32_e32 v40, v10
	v_mov_b32_e32 v14, v11
	v_pk_fma_f32 v[28:29], v[90:91], v[28:29], v[94:95]
	v_cndmask_b32_e64 v27, v31, v45, s[10:11]
	v_cndmask_b32_e64 v31, v35, v47, s[10:11]
	v_cvt_pk_bf16_f32 v238, v8, v9
	v_mul_f32_e32 v35, v8, v8
	v_mul_f32_e32 v37, v9, v9
	v_pk_add_f32 v[8:9], v[38:39], v[12:13]
	v_pk_add_f32 v[12:13], v[40:41], v[14:15]
	v_pk_fma_f32 v[6:7], v[26:27], s[34:35], v[6:7] op_sel_hi:[1,0,1]
	v_pk_fma_f32 v[4:5], v[24:25], s[34:35], v[4:5] op_sel_hi:[1,0,1]
	v_cndmask_b32_e64 v29, v29, v49, s[10:11]
	v_cndmask_b32_e64 v28, v28, v48, s[10:11]
	v_pk_add_f32 v[8:9], v[8:9], v[12:13]
	v_pk_add_f32 v[12:13], v[34:35], v[36:37]
	v_mov_b32_e32 v165, v43
	v_mul_f32_e32 v23, v4, v4
	v_mul_f32_e32 v25, v5, v5
	v_mul_f32_e32 v27, v6, v6
	v_mul_f32_e32 v33, v7, v7
	v_pk_fma_f32 v[28:29], v[28:29], s[34:35], v[2:3] op_sel_hi:[1,0,1]
	v_pk_fma_f32 v[30:31], v[30:31], s[34:35], v[0:1] op_sel_hi:[1,0,1]
	v_pk_add_f32 v[12:13], v[12:13], v[164:165]
	v_mov_b32_e32 v22, v4
	v_mov_b32_e32 v24, v5
	v_mov_b32_e32 v26, v6
	v_mov_b32_e32 v32, v7
	v_mul_f32_e32 v1, v30, v30
	v_mul_f32_e32 v3, v31, v31
	v_mul_f32_e32 v45, v28, v28
	v_mul_f32_e32 v47, v29, v29
	v_pk_add_f32 v[8:9], v[8:9], v[12:13]
	v_pk_add_f32 v[12:13], v[22:23], v[24:25]
	v_pk_add_f32 v[14:15], v[26:27], v[32:33]
	v_mov_b32_e32 v0, v30
	v_mov_b32_e32 v2, v31
	v_mov_b32_e32 v44, v28
	v_mov_b32_e32 v46, v29
	v_pk_add_f32 v[12:13], v[12:13], v[14:15]
	v_pk_add_f32 v[0:1], v[0:1], v[2:3]
	v_pk_add_f32 v[2:3], v[44:45], v[46:47]
	v_pk_add_f32 v[8:9], v[8:9], v[12:13]
	v_pk_add_f32 v[0:1], v[0:1], v[2:3]
	v_cvt_pk_bf16_f32 v240, v4, v5
	v_pk_add_f32 v[0:1], v[8:9], v[0:1]
	ds_bpermute_b32 v2, v148, v0
	ds_bpermute_b32 v3, v148, v1
	v_cvt_pk_bf16_f32 v241, v6, v7
	v_cvt_pk_bf16_f32 v239, v10, v11
	v_cvt_pk_bf16_f32 v242, v30, v31
	s_waitcnt lgkmcnt(0)
	v_pk_add_f32 v[0:1], v[0:1], v[2:3]
	ds_bpermute_b32 v2, v149, v0
	ds_bpermute_b32 v3, v149, v1
	v_cvt_pk_bf16_f32 v243, v28, v29
	s_nop 1
	v_permlane16_swap_b32_e32 v236, v238
	v_permlane16_swap_b32_e32 v237, v239
	v_lshl_add_u64 v[244:245], v[18:19], 0, v[246:247]
	global_store_dwordx4 v[244:245], v[236:239], off
	s_nop 1
	v_permlane16_swap_b32_e32 v240, v242
	v_permlane16_swap_b32_e32 v241, v243
	global_store_dwordx4 v[244:245], v[240:243], off offset:256
	s_and_saveexec_b64 s[50:51], s[8:9]
	s_cbranch_execz .LBB0_1060
	s_waitcnt lgkmcnt(0)
	v_pk_add_f32 v[0:1], v[0:1], v[2:3]
	v_lshlrev_b64 v[2:3], 7, v[16:17]
	v_lshl_add_u64 v[2:3], s[24:25], 0, v[2:3]
	v_lshl_add_u64 v[2:3], s[14:15], 2, v[2:3]
	global_store_dwordx2 v[2:3], v[0:1], off
